# MFMA order in K-loop blocks: both k-steps of an accumulator back to back, adjacent chains share an operand (k order alternates); rest as v6
# speedup vs baseline: 1.0246x; 1.0152x over previous
.LBB0_133:
	s_add_u32 vcc_lo, s0, 0xffffc000
	s_addc_u32 vcc_hi, s1, -1
	v_lshl_add_u64 v[198:199], vcc, 0, v[158:159]
	s_mov_b32 m0, s52
	s_nop 0
	global_load_lds_dwordx4 v[198:199], off
	v_lshl_add_u64 v[198:199], vcc, 0, v[160:161]
	s_mov_b32 m0, s53
	s_nop 0
	global_load_lds_dwordx4 v[198:199], off
	ds_read_b128 v[130:133], v224
	ds_read_b128 v[134:137], v224 offset:1024
	ds_read_b128 v[138:141], v224 offset:2048
	ds_read_b128 v[142:145], v224 offset:3072
	ds_read_b128 v[146:149], v224 offset:16384
	ds_read_b128 v[162:165], v224 offset:17408
	ds_read_b128 v[166:169], v224 offset:18432
	ds_read_b128 v[170:173], v224 offset:19456
	ds_read_b128 v[174:177], v225
	ds_read_b128 v[178:181], v225 offset:1024
	ds_read_b128 v[182:185], v225 offset:2048
	ds_read_b128 v[186:189], v225 offset:3072
	ds_read_b128 v[190:193], v225 offset:4096
	ds_read_b128 v[204:207], v225 offset:5120
	ds_read_b128 v[208:211], v225 offset:6144
	ds_read_b128 v[212:215], v225 offset:7168
	s_add_u32 s4, s0, 0x100
	s_addc_u32 s5, s1, 0
	s_add_i32 s58, 0, 0x10000
	s_cmp_eq_u32 s57, 28
	s_cselect_b32 s35, s27, s5
	s_cselect_b32 s34, s26, s4
	s_cselect_b32 s31, s25, s51
	s_cselect_b32 s30, s37, s50
	s_add_i32 s59, 0, 0x14000
	v_lshl_add_u64 v[198:199], s[0:1], 0, v[158:159]
	s_add_i32 m0, s38, 0xc000
	s_nop 0
	global_load_lds_dwordx4 v[198:199], off
	v_lshl_add_u64 v[198:199], s[0:1], 0, v[160:161]
	s_add_i32 m0, s38, 0xe000
	s_nop 0
	global_load_lds_dwordx4 v[198:199], off
	s_waitcnt vmcnt(8)
	s_waitcnt lgkmcnt(0)
	v_mfma_f32_16x16x32_bf16 v[126:129], v[130:133], v[174:177], v[126:129]
	v_mfma_f32_16x16x32_bf16 v[126:129], v[134:137], v[178:181], v[126:129]
	s_barrier
	s_setprio 1
	v_mfma_f32_16x16x32_bf16 v[122:125], v[142:145], v[178:181], v[122:125]
	v_mfma_f32_16x16x32_bf16 v[122:125], v[138:141], v[174:177], v[122:125]
	v_mfma_f32_16x16x32_bf16 v[106:109], v[138:141], v[182:185], v[106:109]
	v_mfma_f32_16x16x32_bf16 v[106:109], v[142:145], v[186:189], v[106:109]
	v_mfma_f32_16x16x32_bf16 v[110:113], v[134:137], v[186:189], v[110:113]
	v_mfma_f32_16x16x32_bf16 v[110:113], v[130:133], v[182:185], v[110:113]
	v_mfma_f32_16x16x32_bf16 v[94:97], v[130:133], v[190:193], v[94:97]
	v_mfma_f32_16x16x32_bf16 v[94:97], v[134:137], v[204:207], v[94:97]
	v_mfma_f32_16x16x32_bf16 v[90:93], v[142:145], v[204:207], v[90:93]
	v_mfma_f32_16x16x32_bf16 v[90:93], v[138:141], v[190:193], v[90:93]
	v_mfma_f32_16x16x32_bf16 v[74:77], v[138:141], v[208:211], v[74:77]
	v_mfma_f32_16x16x32_bf16 v[74:77], v[142:145], v[212:215], v[74:77]
	v_mfma_f32_16x16x32_bf16 v[78:81], v[134:137], v[212:215], v[78:81]
	v_mfma_f32_16x16x32_bf16 v[78:81], v[130:133], v[208:211], v[78:81]
	v_mfma_f32_16x16x32_bf16 v[118:121], v[146:149], v[174:177], v[118:121]
	v_mfma_f32_16x16x32_bf16 v[118:121], v[162:165], v[178:181], v[118:121]
	v_mfma_f32_16x16x32_bf16 v[114:117], v[170:173], v[178:181], v[114:117]
	v_mfma_f32_16x16x32_bf16 v[114:117], v[166:169], v[174:177], v[114:117]
	v_mfma_f32_16x16x32_bf16 v[98:101], v[166:169], v[182:185], v[98:101]
	v_mfma_f32_16x16x32_bf16 v[98:101], v[170:173], v[186:189], v[98:101]
	v_mfma_f32_16x16x32_bf16 v[102:105], v[162:165], v[186:189], v[102:105]
	v_mfma_f32_16x16x32_bf16 v[102:105], v[146:149], v[182:185], v[102:105]
	v_mfma_f32_16x16x32_bf16 v[86:89], v[146:149], v[190:193], v[86:89]
	v_mfma_f32_16x16x32_bf16 v[86:89], v[162:165], v[204:207], v[86:89]
	v_mfma_f32_16x16x32_bf16 v[82:85], v[170:173], v[204:207], v[82:85]
	v_mfma_f32_16x16x32_bf16 v[82:85], v[166:169], v[190:193], v[82:85]
	v_mfma_f32_16x16x32_bf16 v[66:69], v[166:169], v[208:211], v[66:69]
	v_mfma_f32_16x16x32_bf16 v[66:69], v[170:173], v[212:215], v[66:69]
	v_mfma_f32_16x16x32_bf16 v[70:73], v[162:165], v[212:215], v[70:73]
	v_mfma_f32_16x16x32_bf16 v[70:73], v[146:149], v[208:211], v[70:73]
	s_setprio 0
	s_barrier
	ds_read_b128 v[174:177], v225 offset:16384
	ds_read_b128 v[178:181], v225 offset:17408
	ds_read_b128 v[182:185], v225 offset:18432
	ds_read_b128 v[186:189], v225 offset:19456
	ds_read_b128 v[190:193], v225 offset:20480
	ds_read_b128 v[204:207], v225 offset:21504
	ds_read_b128 v[208:211], v225 offset:22528
	ds_read_b128 v[212:215], v225 offset:23552
	s_add_i32 s0, s58, s15
	v_lshl_add_u64 v[198:199], s[30:31], 0, v[152:153]
	s_mov_b32 m0, s0
	s_nop 0
	global_load_lds_dwordx4 v[198:199], off
	s_add_i32 m0, s0, 0x2000
	s_add_u32 s0, s30, 0x80000
	v_lshl_add_u64 v[216:217], s[30:31], 0, v[156:157]
	s_addc_u32 s1, s31, 0
	s_add_i32 s58, s59, s15
	global_load_lds_dwordx4 v[216:217], off
	v_lshl_add_u64 v[218:219], s[0:1], 0, v[152:153]
	s_mov_b32 m0, s58
	v_lshl_add_u64 v[220:221], s[34:35], 0, v[154:155]
	global_load_lds_dwordx4 v[218:219], off
	v_lshl_add_u64 v[218:219], s[0:1], 0, v[156:157]
	s_add_i32 m0, s58, 0x2000
	s_nop 0
	global_load_lds_dwordx4 v[218:219], off
	v_lshl_add_u64 v[218:219], s[34:35], 0, v[150:151]
	s_waitcnt vmcnt(6)
	s_waitcnt lgkmcnt(0)
	v_mfma_f32_16x16x32_bf16 v[62:65], v[130:133], v[174:177], v[62:65]
	v_mfma_f32_16x16x32_bf16 v[62:65], v[134:137], v[178:181], v[62:65]
	s_barrier
	s_setprio 1
	v_mfma_f32_16x16x32_bf16 v[58:61], v[142:145], v[178:181], v[58:61]
	v_mfma_f32_16x16x32_bf16 v[58:61], v[138:141], v[174:177], v[58:61]
	v_mfma_f32_16x16x32_bf16 v[42:45], v[138:141], v[182:185], v[42:45]
	v_mfma_f32_16x16x32_bf16 v[42:45], v[142:145], v[186:189], v[42:45]
	v_mfma_f32_16x16x32_bf16 v[46:49], v[134:137], v[186:189], v[46:49]
	v_mfma_f32_16x16x32_bf16 v[46:49], v[130:133], v[182:185], v[46:49]
	v_mfma_f32_16x16x32_bf16 v[30:33], v[130:133], v[190:193], v[30:33]
	v_mfma_f32_16x16x32_bf16 v[30:33], v[134:137], v[204:207], v[30:33]
	v_mfma_f32_16x16x32_bf16 v[26:29], v[142:145], v[204:207], v[26:29]
	v_mfma_f32_16x16x32_bf16 v[26:29], v[138:141], v[190:193], v[26:29]
	v_mfma_f32_16x16x32_bf16 v[10:13], v[138:141], v[208:211], v[10:13]
	v_mfma_f32_16x16x32_bf16 v[10:13], v[142:145], v[212:215], v[10:13]
	v_mfma_f32_16x16x32_bf16 v[14:17], v[134:137], v[212:215], v[14:17]
	v_mfma_f32_16x16x32_bf16 v[14:17], v[130:133], v[208:211], v[14:17]
	v_mfma_f32_16x16x32_bf16 v[54:57], v[146:149], v[174:177], v[54:57]
	v_mfma_f32_16x16x32_bf16 v[54:57], v[162:165], v[178:181], v[54:57]
	v_mfma_f32_16x16x32_bf16 v[50:53], v[170:173], v[178:181], v[50:53]
	v_mfma_f32_16x16x32_bf16 v[50:53], v[166:169], v[174:177], v[50:53]
	v_mfma_f32_16x16x32_bf16 v[34:37], v[166:169], v[182:185], v[34:37]
	v_mfma_f32_16x16x32_bf16 v[34:37], v[170:173], v[186:189], v[34:37]
	v_mfma_f32_16x16x32_bf16 v[38:41], v[162:165], v[186:189], v[38:41]
	v_mfma_f32_16x16x32_bf16 v[38:41], v[146:149], v[182:185], v[38:41]
	v_mfma_f32_16x16x32_bf16 v[22:25], v[146:149], v[190:193], v[22:25]
	v_mfma_f32_16x16x32_bf16 v[22:25], v[162:165], v[204:207], v[22:25]
	v_mfma_f32_16x16x32_bf16 v[18:21], v[170:173], v[204:207], v[18:21]
	v_mfma_f32_16x16x32_bf16 v[18:21], v[166:169], v[190:193], v[18:21]
	v_mfma_f32_16x16x32_bf16 v[2:5], v[166:169], v[208:211], v[2:5]
	v_mfma_f32_16x16x32_bf16 v[2:5], v[170:173], v[212:215], v[2:5]
	v_mfma_f32_16x16x32_bf16 v[6:9], v[162:165], v[212:215], v[6:9]
	v_mfma_f32_16x16x32_bf16 v[6:9], v[146:149], v[208:211], v[6:9]
	s_setprio 0
	s_barrier
	s_mov_b32 m0, s38
	s_nop 0
	global_load_lds_dwordx4 v[218:219], off
	s_mov_b32 m0, s39
	s_nop 0
	global_load_lds_dwordx4 v[220:221], off
	ds_read_b128 v[130:133], v224 offset:32768
	ds_read_b128 v[134:137], v224 offset:33792
	ds_read_b128 v[138:141], v224 offset:34816
	ds_read_b128 v[142:145], v224 offset:35840
	ds_read_b128 v[146:149], v224 offset:49152
	ds_read_b128 v[162:165], v224 offset:50176
	ds_read_b128 v[166:169], v224 offset:51200
	ds_read_b128 v[170:173], v224 offset:52224
	ds_read_b128 v[174:177], v225 offset:32768
	ds_read_b128 v[178:181], v225 offset:33792
	ds_read_b128 v[182:185], v225 offset:34816
	ds_read_b128 v[186:189], v225 offset:35840
	ds_read_b128 v[190:193], v225 offset:36864
	ds_read_b128 v[204:207], v225 offset:37888
	ds_read_b128 v[208:211], v225 offset:38912
	ds_read_b128 v[212:215], v225 offset:39936
	s_add_i32 s58, 0, 0x18000
	s_add_i32 s59, 0, 0x1c000
	s_add_u32 s0, s34, 0x4000
	s_addc_u32 s1, s35, 0
	s_mov_b32 m0, s40
	v_lshl_add_u64 v[222:223], s[0:1], 0, v[150:151]
	global_load_lds_dwordx4 v[222:223], off
	v_lshl_add_u64 v[222:223], s[0:1], 0, v[154:155]
	s_mov_b32 m0, s41
	s_nop 0
	global_load_lds_dwordx4 v[222:223], off
	s_waitcnt vmcnt(8)
	s_waitcnt lgkmcnt(0)
	v_mfma_f32_16x16x32_bf16 v[126:129], v[130:133], v[174:177], v[126:129]
	v_mfma_f32_16x16x32_bf16 v[126:129], v[134:137], v[178:181], v[126:129]
	s_barrier
	s_setprio 1
	v_mfma_f32_16x16x32_bf16 v[122:125], v[142:145], v[178:181], v[122:125]
	v_mfma_f32_16x16x32_bf16 v[122:125], v[138:141], v[174:177], v[122:125]
	v_mfma_f32_16x16x32_bf16 v[106:109], v[138:141], v[182:185], v[106:109]
	v_mfma_f32_16x16x32_bf16 v[106:109], v[142:145], v[186:189], v[106:109]
	v_mfma_f32_16x16x32_bf16 v[110:113], v[134:137], v[186:189], v[110:113]
	v_mfma_f32_16x16x32_bf16 v[110:113], v[130:133], v[182:185], v[110:113]
	v_mfma_f32_16x16x32_bf16 v[94:97], v[130:133], v[190:193], v[94:97]
	v_mfma_f32_16x16x32_bf16 v[94:97], v[134:137], v[204:207], v[94:97]
	v_mfma_f32_16x16x32_bf16 v[90:93], v[142:145], v[204:207], v[90:93]
	v_mfma_f32_16x16x32_bf16 v[90:93], v[138:141], v[190:193], v[90:93]
	v_mfma_f32_16x16x32_bf16 v[74:77], v[138:141], v[208:211], v[74:77]
	v_mfma_f32_16x16x32_bf16 v[74:77], v[142:145], v[212:215], v[74:77]
	v_mfma_f32_16x16x32_bf16 v[78:81], v[134:137], v[212:215], v[78:81]
	v_mfma_f32_16x16x32_bf16 v[78:81], v[130:133], v[208:211], v[78:81]
	v_mfma_f32_16x16x32_bf16 v[118:121], v[146:149], v[174:177], v[118:121]
	v_mfma_f32_16x16x32_bf16 v[118:121], v[162:165], v[178:181], v[118:121]
	v_mfma_f32_16x16x32_bf16 v[114:117], v[170:173], v[178:181], v[114:117]
	v_mfma_f32_16x16x32_bf16 v[114:117], v[166:169], v[174:177], v[114:117]
	v_mfma_f32_16x16x32_bf16 v[98:101], v[166:169], v[182:185], v[98:101]
	v_mfma_f32_16x16x32_bf16 v[98:101], v[170:173], v[186:189], v[98:101]
	v_mfma_f32_16x16x32_bf16 v[102:105], v[162:165], v[186:189], v[102:105]
	v_mfma_f32_16x16x32_bf16 v[102:105], v[146:149], v[182:185], v[102:105]
	v_mfma_f32_16x16x32_bf16 v[86:89], v[146:149], v[190:193], v[86:89]
	v_mfma_f32_16x16x32_bf16 v[86:89], v[162:165], v[204:207], v[86:89]
	v_mfma_f32_16x16x32_bf16 v[82:85], v[170:173], v[204:207], v[82:85]
	v_mfma_f32_16x16x32_bf16 v[82:85], v[166:169], v[190:193], v[82:85]
	v_mfma_f32_16x16x32_bf16 v[66:69], v[166:169], v[208:211], v[66:69]
	v_mfma_f32_16x16x32_bf16 v[66:69], v[170:173], v[212:215], v[66:69]
	v_mfma_f32_16x16x32_bf16 v[70:73], v[162:165], v[212:215], v[70:73]
	v_mfma_f32_16x16x32_bf16 v[70:73], v[146:149], v[208:211], v[70:73]
	s_setprio 0
	s_barrier
	ds_read_b128 v[174:177], v225 offset:49152
	ds_read_b128 v[178:181], v225 offset:50176
	ds_read_b128 v[182:185], v225 offset:51200
	ds_read_b128 v[186:189], v225 offset:52224
	ds_read_b128 v[190:193], v225 offset:53248
	ds_read_b128 v[204:207], v225 offset:54272
	ds_read_b128 v[208:211], v225 offset:55296
	ds_read_b128 v[212:215], v225 offset:56320
	s_add_i32 s0, s58, s15
	v_lshl_add_u64 v[198:199], v[198:199], 0, s[94:95]
	s_mov_b32 m0, s0
	s_nop 0
	global_load_lds_dwordx4 v[198:199], off
	s_add_i32 m0, s0, 0x2000
	s_add_u32 s0, s30, 0x80080
	v_lshl_add_u64 v[198:199], v[216:217], 0, s[94:95]
	s_addc_u32 s1, s31, 0
	s_add_i32 s30, s59, s15
	global_load_lds_dwordx4 v[198:199], off
	v_lshl_add_u64 v[198:199], s[0:1], 0, v[152:153]
	s_mov_b32 m0, s30
	s_nop 0
	global_load_lds_dwordx4 v[198:199], off
	v_lshl_add_u64 v[198:199], s[0:1], 0, v[156:157]
	s_add_i32 m0, s30, 0x2000
	s_nop 0
	global_load_lds_dwordx4 v[198:199], off
	s_waitcnt vmcnt(6)
	s_waitcnt lgkmcnt(0)
	v_mfma_f32_16x16x32_bf16 v[62:65], v[130:133], v[174:177], v[62:65]
	v_mfma_f32_16x16x32_bf16 v[62:65], v[134:137], v[178:181], v[62:65]
	s_barrier
	s_setprio 1
	v_mfma_f32_16x16x32_bf16 v[58:61], v[142:145], v[178:181], v[58:61]
	v_mfma_f32_16x16x32_bf16 v[58:61], v[138:141], v[174:177], v[58:61]
	v_mfma_f32_16x16x32_bf16 v[42:45], v[138:141], v[182:185], v[42:45]
	v_mfma_f32_16x16x32_bf16 v[42:45], v[142:145], v[186:189], v[42:45]
	v_mfma_f32_16x16x32_bf16 v[46:49], v[134:137], v[186:189], v[46:49]
	v_mfma_f32_16x16x32_bf16 v[46:49], v[130:133], v[182:185], v[46:49]
	v_mfma_f32_16x16x32_bf16 v[30:33], v[130:133], v[190:193], v[30:33]
	v_mfma_f32_16x16x32_bf16 v[30:33], v[134:137], v[204:207], v[30:33]
	v_mfma_f32_16x16x32_bf16 v[26:29], v[142:145], v[204:207], v[26:29]
	v_mfma_f32_16x16x32_bf16 v[26:29], v[138:141], v[190:193], v[26:29]
	v_mfma_f32_16x16x32_bf16 v[10:13], v[138:141], v[208:211], v[10:13]
	v_mfma_f32_16x16x32_bf16 v[10:13], v[142:145], v[212:215], v[10:13]
	s_add_i32 s57, s57, 2
	v_mfma_f32_16x16x32_bf16 v[14:17], v[134:137], v[212:215], v[14:17]
	v_mfma_f32_16x16x32_bf16 v[14:17], v[130:133], v[208:211], v[14:17]
	s_add_u32 s50, s50, 0x100
	v_mfma_f32_16x16x32_bf16 v[54:57], v[146:149], v[174:177], v[54:57]
	v_mfma_f32_16x16x32_bf16 v[54:57], v[162:165], v[178:181], v[54:57]
	s_addc_u32 s51, s51, 0
	v_mfma_f32_16x16x32_bf16 v[50:53], v[170:173], v[178:181], v[50:53]
	v_mfma_f32_16x16x32_bf16 v[50:53], v[166:169], v[174:177], v[50:53]
	s_cmp_gt_u32 s57, 29
	v_mfma_f32_16x16x32_bf16 v[34:37], v[166:169], v[182:185], v[34:37]
	v_mfma_f32_16x16x32_bf16 v[34:37], v[170:173], v[186:189], v[34:37]
	s_mov_b64 s[0:1], s[4:5]
	v_mfma_f32_16x16x32_bf16 v[38:41], v[162:165], v[186:189], v[38:41]
	v_mfma_f32_16x16x32_bf16 v[38:41], v[146:149], v[182:185], v[38:41]
	v_mfma_f32_16x16x32_bf16 v[22:25], v[146:149], v[190:193], v[22:25]
	v_mfma_f32_16x16x32_bf16 v[22:25], v[162:165], v[204:207], v[22:25]
	v_mfma_f32_16x16x32_bf16 v[18:21], v[170:173], v[204:207], v[18:21]
	v_mfma_f32_16x16x32_bf16 v[18:21], v[166:169], v[190:193], v[18:21]
	v_mfma_f32_16x16x32_bf16 v[2:5], v[166:169], v[208:211], v[2:5]
	v_mfma_f32_16x16x32_bf16 v[2:5], v[170:173], v[212:215], v[2:5]
	v_mfma_f32_16x16x32_bf16 v[6:9], v[162:165], v[212:215], v[6:9]
	v_mfma_f32_16x16x32_bf16 v[6:9], v[146:149], v[208:211], v[6:9]
	s_setprio 0
	s_barrier
	s_cbranch_scc0 .LBB0_133
	s_and_b64 vcc, exec, s[16:17]
	s_cbranch_vccz .LBB0_136
	s_barrier

.LBB0_305:
	s_add_u32 vcc_lo, s0, 0xffffc000
	s_addc_u32 vcc_hi, s1, -1
	v_lshl_add_u64 v[198:199], vcc, 0, v[178:179]
	s_mov_b32 m0, s62
	s_nop 0
	global_load_lds_dwordx4 v[198:199], off
	v_lshl_add_u64 v[198:199], vcc, 0, v[180:181]
	s_mov_b32 m0, s63
	s_nop 0
	global_load_lds_dwordx4 v[198:199], off
	ds_read_b128 v[130:133], v226
	ds_read_b128 v[134:137], v226 offset:1024
	ds_read_b128 v[138:141], v226 offset:2048
	ds_read_b128 v[142:145], v226 offset:3072
	ds_read_b128 v[146:149], v226 offset:16384
	ds_read_b128 v[150:153], v226 offset:17408
	ds_read_b128 v[154:157], v226 offset:18432
	ds_read_b128 v[158:161], v226 offset:19456
	ds_read_b128 v[162:165], v227
	ds_read_b128 v[166:169], v227 offset:1024
	ds_read_b128 v[182:185], v227 offset:2048
	ds_read_b128 v[186:189], v227 offset:3072
	ds_read_b128 v[190:193], v227 offset:4096
	ds_read_b128 v[204:207], v227 offset:5120
	ds_read_b128 v[208:211], v227 offset:6144
	ds_read_b128 v[212:215], v227 offset:7168
	s_add_i32 s71, s38, 2
	s_add_u32 s4, s0, 0x100
	s_addc_u32 s5, s1, 0
	s_add_i32 s73, 0, 0x10000
	s_cmp_eq_u32 s37, s38
	s_cselect_b32 s41, s31, s5
	s_cselect_b32 s40, s30, s4
	s_cselect_b32 s39, s25, s70
	s_cselect_b32 s38, s27, s51
	s_add_i32 s75, 0, 0x14000
	v_lshl_add_u64 v[198:199], s[0:1], 0, v[178:179]
	s_add_i32 m0, s56, 0xc000
	s_nop 0
	global_load_lds_dwordx4 v[198:199], off
	v_lshl_add_u64 v[198:199], s[0:1], 0, v[180:181]
	s_add_i32 m0, s56, 0xe000
	s_nop 0
	global_load_lds_dwordx4 v[198:199], off
	s_waitcnt vmcnt(8)
	s_waitcnt lgkmcnt(0)
	v_mfma_f32_16x16x32_bf16 v[126:129], v[130:133], v[162:165], v[126:129]
	v_mfma_f32_16x16x32_bf16 v[126:129], v[134:137], v[166:169], v[126:129]
	s_barrier
	s_setprio 1
	v_mfma_f32_16x16x32_bf16 v[122:125], v[142:145], v[166:169], v[122:125]
	v_mfma_f32_16x16x32_bf16 v[122:125], v[138:141], v[162:165], v[122:125]
	v_mfma_f32_16x16x32_bf16 v[106:109], v[138:141], v[182:185], v[106:109]
	v_mfma_f32_16x16x32_bf16 v[106:109], v[142:145], v[186:189], v[106:109]
	v_mfma_f32_16x16x32_bf16 v[110:113], v[134:137], v[186:189], v[110:113]
	v_mfma_f32_16x16x32_bf16 v[110:113], v[130:133], v[182:185], v[110:113]
	v_mfma_f32_16x16x32_bf16 v[94:97], v[130:133], v[190:193], v[94:97]
	v_mfma_f32_16x16x32_bf16 v[94:97], v[134:137], v[204:207], v[94:97]
	v_mfma_f32_16x16x32_bf16 v[90:93], v[142:145], v[204:207], v[90:93]
	v_mfma_f32_16x16x32_bf16 v[90:93], v[138:141], v[190:193], v[90:93]
	v_mfma_f32_16x16x32_bf16 v[74:77], v[138:141], v[208:211], v[74:77]
	v_mfma_f32_16x16x32_bf16 v[74:77], v[142:145], v[212:215], v[74:77]
	v_mfma_f32_16x16x32_bf16 v[78:81], v[134:137], v[212:215], v[78:81]
	v_mfma_f32_16x16x32_bf16 v[78:81], v[130:133], v[208:211], v[78:81]
	v_mfma_f32_16x16x32_bf16 v[118:121], v[146:149], v[162:165], v[118:121]
	v_mfma_f32_16x16x32_bf16 v[118:121], v[150:153], v[166:169], v[118:121]
	v_mfma_f32_16x16x32_bf16 v[114:117], v[158:161], v[166:169], v[114:117]
	v_mfma_f32_16x16x32_bf16 v[114:117], v[154:157], v[162:165], v[114:117]
	v_mfma_f32_16x16x32_bf16 v[98:101], v[154:157], v[182:185], v[98:101]
	v_mfma_f32_16x16x32_bf16 v[98:101], v[158:161], v[186:189], v[98:101]
	v_mfma_f32_16x16x32_bf16 v[102:105], v[150:153], v[186:189], v[102:105]
	v_mfma_f32_16x16x32_bf16 v[102:105], v[146:149], v[182:185], v[102:105]
	v_mfma_f32_16x16x32_bf16 v[86:89], v[146:149], v[190:193], v[86:89]
	v_mfma_f32_16x16x32_bf16 v[86:89], v[150:153], v[204:207], v[86:89]
	v_mfma_f32_16x16x32_bf16 v[82:85], v[158:161], v[204:207], v[82:85]
	v_mfma_f32_16x16x32_bf16 v[82:85], v[154:157], v[190:193], v[82:85]
	v_mfma_f32_16x16x32_bf16 v[66:69], v[154:157], v[208:211], v[66:69]
	v_mfma_f32_16x16x32_bf16 v[66:69], v[158:161], v[212:215], v[66:69]
	v_mfma_f32_16x16x32_bf16 v[70:73], v[150:153], v[212:215], v[70:73]
	v_mfma_f32_16x16x32_bf16 v[70:73], v[146:149], v[208:211], v[70:73]
	s_setprio 0
	s_barrier
	ds_read_b128 v[162:165], v227 offset:16384
	ds_read_b128 v[166:169], v227 offset:17408
	ds_read_b128 v[182:185], v227 offset:18432
	ds_read_b128 v[186:189], v227 offset:19456
	ds_read_b128 v[190:193], v227 offset:20480
	ds_read_b128 v[204:207], v227 offset:21504
	ds_read_b128 v[208:211], v227 offset:22528
	ds_read_b128 v[212:215], v227 offset:23552
	s_add_i32 s0, s73, s15
	v_lshl_add_u64 v[198:199], s[38:39], 0, v[172:173]
	s_mov_b32 m0, s0
	s_nop 0
	global_load_lds_dwordx4 v[198:199], off
	s_add_i32 m0, s0, 0x2000
	s_add_u32 s0, s38, 0x80000
	v_lshl_add_u64 v[216:217], s[38:39], 0, v[176:177]
	s_addc_u32 s1, s39, 0
	s_add_i32 s73, s75, s15
	global_load_lds_dwordx4 v[216:217], off
	v_lshl_add_u64 v[218:219], s[0:1], 0, v[172:173]
	s_mov_b32 m0, s73
	v_lshl_add_u64 v[220:221], s[40:41], 0, v[174:175]
	global_load_lds_dwordx4 v[218:219], off
	v_lshl_add_u64 v[218:219], s[0:1], 0, v[176:177]
	s_add_i32 m0, s73, 0x2000
	s_nop 0
	global_load_lds_dwordx4 v[218:219], off
	v_lshl_add_u64 v[218:219], s[40:41], 0, v[170:171]
	s_waitcnt vmcnt(6)
	s_waitcnt lgkmcnt(0)
	v_mfma_f32_16x16x32_bf16 v[62:65], v[130:133], v[162:165], v[62:65]
	v_mfma_f32_16x16x32_bf16 v[62:65], v[134:137], v[166:169], v[62:65]
	s_barrier
	s_setprio 1
	v_mfma_f32_16x16x32_bf16 v[58:61], v[142:145], v[166:169], v[58:61]
	v_mfma_f32_16x16x32_bf16 v[58:61], v[138:141], v[162:165], v[58:61]
	v_mfma_f32_16x16x32_bf16 v[42:45], v[138:141], v[182:185], v[42:45]
	v_mfma_f32_16x16x32_bf16 v[42:45], v[142:145], v[186:189], v[42:45]
	v_mfma_f32_16x16x32_bf16 v[46:49], v[134:137], v[186:189], v[46:49]
	v_mfma_f32_16x16x32_bf16 v[46:49], v[130:133], v[182:185], v[46:49]
	v_mfma_f32_16x16x32_bf16 v[30:33], v[130:133], v[190:193], v[30:33]
	v_mfma_f32_16x16x32_bf16 v[30:33], v[134:137], v[204:207], v[30:33]
	v_mfma_f32_16x16x32_bf16 v[26:29], v[142:145], v[204:207], v[26:29]
	v_mfma_f32_16x16x32_bf16 v[26:29], v[138:141], v[190:193], v[26:29]
	v_mfma_f32_16x16x32_bf16 v[10:13], v[138:141], v[208:211], v[10:13]
	v_mfma_f32_16x16x32_bf16 v[10:13], v[142:145], v[212:215], v[10:13]
	v_mfma_f32_16x16x32_bf16 v[14:17], v[134:137], v[212:215], v[14:17]
	v_mfma_f32_16x16x32_bf16 v[14:17], v[130:133], v[208:211], v[14:17]
	v_mfma_f32_16x16x32_bf16 v[54:57], v[146:149], v[162:165], v[54:57]
	v_mfma_f32_16x16x32_bf16 v[54:57], v[150:153], v[166:169], v[54:57]
	v_mfma_f32_16x16x32_bf16 v[50:53], v[158:161], v[166:169], v[50:53]
	v_mfma_f32_16x16x32_bf16 v[50:53], v[154:157], v[162:165], v[50:53]
	v_mfma_f32_16x16x32_bf16 v[34:37], v[154:157], v[182:185], v[34:37]
	v_mfma_f32_16x16x32_bf16 v[34:37], v[158:161], v[186:189], v[34:37]
	v_mfma_f32_16x16x32_bf16 v[38:41], v[150:153], v[186:189], v[38:41]
	v_mfma_f32_16x16x32_bf16 v[38:41], v[146:149], v[182:185], v[38:41]
	v_mfma_f32_16x16x32_bf16 v[22:25], v[146:149], v[190:193], v[22:25]
	v_mfma_f32_16x16x32_bf16 v[22:25], v[150:153], v[204:207], v[22:25]
	v_mfma_f32_16x16x32_bf16 v[18:21], v[158:161], v[204:207], v[18:21]
	v_mfma_f32_16x16x32_bf16 v[18:21], v[154:157], v[190:193], v[18:21]
	v_mfma_f32_16x16x32_bf16 v[2:5], v[154:157], v[208:211], v[2:5]
	v_mfma_f32_16x16x32_bf16 v[2:5], v[158:161], v[212:215], v[2:5]
	v_mfma_f32_16x16x32_bf16 v[6:9], v[150:153], v[212:215], v[6:9]
	v_mfma_f32_16x16x32_bf16 v[6:9], v[146:149], v[208:211], v[6:9]
	s_setprio 0
	s_barrier
	s_mov_b32 m0, s56
	s_nop 0
	global_load_lds_dwordx4 v[218:219], off
	s_mov_b32 m0, s57
	s_nop 0
	global_load_lds_dwordx4 v[220:221], off
	ds_read_b128 v[130:133], v226 offset:32768
	ds_read_b128 v[134:137], v226 offset:33792
	ds_read_b128 v[138:141], v226 offset:34816
	ds_read_b128 v[142:145], v226 offset:35840
	ds_read_b128 v[146:149], v226 offset:49152
	ds_read_b128 v[150:153], v226 offset:50176
	ds_read_b128 v[154:157], v226 offset:51200
	ds_read_b128 v[158:161], v226 offset:52224
	ds_read_b128 v[162:165], v227 offset:32768
	ds_read_b128 v[166:169], v227 offset:33792
	ds_read_b128 v[182:185], v227 offset:34816
	ds_read_b128 v[186:189], v227 offset:35840
	ds_read_b128 v[190:193], v227 offset:36864
	ds_read_b128 v[204:207], v227 offset:37888
	ds_read_b128 v[208:211], v227 offset:38912
	ds_read_b128 v[212:215], v227 offset:39936
	s_add_i32 s73, 0, 0x18000
	s_add_i32 s75, 0, 0x1c000
	s_add_u32 s0, s40, 0x4000
	s_addc_u32 s1, s41, 0
	s_mov_b32 m0, s58
	v_lshl_add_u64 v[222:223], s[0:1], 0, v[170:171]
	global_load_lds_dwordx4 v[222:223], off
	v_lshl_add_u64 v[222:223], s[0:1], 0, v[174:175]
	s_mov_b32 m0, s59
	s_nop 0
	global_load_lds_dwordx4 v[222:223], off
	s_waitcnt vmcnt(8)
	s_waitcnt lgkmcnt(0)
	v_mfma_f32_16x16x32_bf16 v[126:129], v[130:133], v[162:165], v[126:129]
	v_mfma_f32_16x16x32_bf16 v[126:129], v[134:137], v[166:169], v[126:129]
	s_barrier
	s_setprio 1
	v_mfma_f32_16x16x32_bf16 v[122:125], v[142:145], v[166:169], v[122:125]
	v_mfma_f32_16x16x32_bf16 v[122:125], v[138:141], v[162:165], v[122:125]
	v_mfma_f32_16x16x32_bf16 v[106:109], v[138:141], v[182:185], v[106:109]
	v_mfma_f32_16x16x32_bf16 v[106:109], v[142:145], v[186:189], v[106:109]
	v_mfma_f32_16x16x32_bf16 v[110:113], v[134:137], v[186:189], v[110:113]
	v_mfma_f32_16x16x32_bf16 v[110:113], v[130:133], v[182:185], v[110:113]
	v_mfma_f32_16x16x32_bf16 v[94:97], v[130:133], v[190:193], v[94:97]
	v_mfma_f32_16x16x32_bf16 v[94:97], v[134:137], v[204:207], v[94:97]
	v_mfma_f32_16x16x32_bf16 v[90:93], v[142:145], v[204:207], v[90:93]
	v_mfma_f32_16x16x32_bf16 v[90:93], v[138:141], v[190:193], v[90:93]
	v_mfma_f32_16x16x32_bf16 v[74:77], v[138:141], v[208:211], v[74:77]
	v_mfma_f32_16x16x32_bf16 v[74:77], v[142:145], v[212:215], v[74:77]
	v_mfma_f32_16x16x32_bf16 v[78:81], v[134:137], v[212:215], v[78:81]
	v_mfma_f32_16x16x32_bf16 v[78:81], v[130:133], v[208:211], v[78:81]
	v_mfma_f32_16x16x32_bf16 v[118:121], v[146:149], v[162:165], v[118:121]
	v_mfma_f32_16x16x32_bf16 v[118:121], v[150:153], v[166:169], v[118:121]
	v_mfma_f32_16x16x32_bf16 v[114:117], v[158:161], v[166:169], v[114:117]
	v_mfma_f32_16x16x32_bf16 v[114:117], v[154:157], v[162:165], v[114:117]
	v_mfma_f32_16x16x32_bf16 v[98:101], v[154:157], v[182:185], v[98:101]
	v_mfma_f32_16x16x32_bf16 v[98:101], v[158:161], v[186:189], v[98:101]
	v_mfma_f32_16x16x32_bf16 v[102:105], v[150:153], v[186:189], v[102:105]
	v_mfma_f32_16x16x32_bf16 v[102:105], v[146:149], v[182:185], v[102:105]
	v_mfma_f32_16x16x32_bf16 v[86:89], v[146:149], v[190:193], v[86:89]
	v_mfma_f32_16x16x32_bf16 v[86:89], v[150:153], v[204:207], v[86:89]
	v_mfma_f32_16x16x32_bf16 v[82:85], v[158:161], v[204:207], v[82:85]
	v_mfma_f32_16x16x32_bf16 v[82:85], v[154:157], v[190:193], v[82:85]
	v_mfma_f32_16x16x32_bf16 v[66:69], v[154:157], v[208:211], v[66:69]
	v_mfma_f32_16x16x32_bf16 v[66:69], v[158:161], v[212:215], v[66:69]
	v_mfma_f32_16x16x32_bf16 v[70:73], v[150:153], v[212:215], v[70:73]
	v_mfma_f32_16x16x32_bf16 v[70:73], v[146:149], v[208:211], v[70:73]
	s_setprio 0
	s_barrier
	ds_read_b128 v[162:165], v227 offset:49152
	ds_read_b128 v[166:169], v227 offset:50176
	ds_read_b128 v[182:185], v227 offset:51200
	ds_read_b128 v[186:189], v227 offset:52224
	ds_read_b128 v[190:193], v227 offset:53248
	ds_read_b128 v[204:207], v227 offset:54272
	ds_read_b128 v[208:211], v227 offset:55296
	ds_read_b128 v[212:215], v227 offset:56320
	s_add_i32 s0, s73, s15
	v_lshl_add_u64 v[198:199], v[198:199], 0, s[94:95]
	s_mov_b32 m0, s0
	s_nop 0
	global_load_lds_dwordx4 v[198:199], off
	s_add_i32 m0, s0, 0x2000
	s_add_u32 s0, s38, 0x80080
	v_lshl_add_u64 v[198:199], v[216:217], 0, s[94:95]
	s_addc_u32 s1, s39, 0
	s_add_i32 s38, s75, s15
	global_load_lds_dwordx4 v[198:199], off
	v_lshl_add_u64 v[198:199], s[0:1], 0, v[172:173]
	s_mov_b32 m0, s38
	s_nop 0
	global_load_lds_dwordx4 v[198:199], off
	v_lshl_add_u64 v[198:199], s[0:1], 0, v[176:177]
	s_add_i32 m0, s38, 0x2000
	s_nop 0
	global_load_lds_dwordx4 v[198:199], off
	s_waitcnt vmcnt(6)
	s_waitcnt lgkmcnt(0)
	v_mfma_f32_16x16x32_bf16 v[62:65], v[130:133], v[162:165], v[62:65]
	v_mfma_f32_16x16x32_bf16 v[62:65], v[134:137], v[166:169], v[62:65]
	s_barrier
	s_setprio 1
	v_mfma_f32_16x16x32_bf16 v[58:61], v[142:145], v[166:169], v[58:61]
	v_mfma_f32_16x16x32_bf16 v[58:61], v[138:141], v[162:165], v[58:61]
	v_mfma_f32_16x16x32_bf16 v[42:45], v[138:141], v[182:185], v[42:45]
	v_mfma_f32_16x16x32_bf16 v[42:45], v[142:145], v[186:189], v[42:45]
	v_mfma_f32_16x16x32_bf16 v[46:49], v[134:137], v[186:189], v[46:49]
	v_mfma_f32_16x16x32_bf16 v[46:49], v[130:133], v[182:185], v[46:49]
	v_mfma_f32_16x16x32_bf16 v[30:33], v[130:133], v[190:193], v[30:33]
	v_mfma_f32_16x16x32_bf16 v[30:33], v[134:137], v[204:207], v[30:33]
	v_mfma_f32_16x16x32_bf16 v[26:29], v[142:145], v[204:207], v[26:29]
	v_mfma_f32_16x16x32_bf16 v[26:29], v[138:141], v[190:193], v[26:29]
	v_mfma_f32_16x16x32_bf16 v[10:13], v[138:141], v[208:211], v[10:13]
	v_mfma_f32_16x16x32_bf16 v[10:13], v[142:145], v[212:215], v[10:13]
	s_add_u32 s51, s51, 0x100
	v_mfma_f32_16x16x32_bf16 v[14:17], v[134:137], v[212:215], v[14:17]
	v_mfma_f32_16x16x32_bf16 v[14:17], v[130:133], v[208:211], v[14:17]
	s_addc_u32 s70, s70, 0
	v_mfma_f32_16x16x32_bf16 v[54:57], v[146:149], v[162:165], v[54:57]
	v_mfma_f32_16x16x32_bf16 v[54:57], v[150:153], v[166:169], v[54:57]
	s_cmp_ge_i32 s71, s35
	v_mfma_f32_16x16x32_bf16 v[50:53], v[158:161], v[166:169], v[50:53]
	v_mfma_f32_16x16x32_bf16 v[50:53], v[154:157], v[162:165], v[50:53]
	s_mov_b64 s[0:1], s[4:5]
	v_mfma_f32_16x16x32_bf16 v[34:37], v[154:157], v[182:185], v[34:37]
	v_mfma_f32_16x16x32_bf16 v[34:37], v[158:161], v[186:189], v[34:37]
	s_mov_b32 s38, s71
	v_mfma_f32_16x16x32_bf16 v[38:41], v[150:153], v[186:189], v[38:41]
	v_mfma_f32_16x16x32_bf16 v[38:41], v[146:149], v[182:185], v[38:41]
	v_mfma_f32_16x16x32_bf16 v[22:25], v[146:149], v[190:193], v[22:25]
	v_mfma_f32_16x16x32_bf16 v[22:25], v[150:153], v[204:207], v[22:25]
	v_mfma_f32_16x16x32_bf16 v[18:21], v[158:161], v[204:207], v[18:21]
	v_mfma_f32_16x16x32_bf16 v[18:21], v[154:157], v[190:193], v[18:21]
	v_mfma_f32_16x16x32_bf16 v[2:5], v[154:157], v[208:211], v[2:5]
	v_mfma_f32_16x16x32_bf16 v[2:5], v[158:161], v[212:215], v[2:5]
	v_mfma_f32_16x16x32_bf16 v[6:9], v[150:153], v[212:215], v[6:9]
	v_mfma_f32_16x16x32_bf16 v[6:9], v[146:149], v[208:211], v[6:9]
	s_setprio 0
	s_barrier
	s_cbranch_scc0 .LBB0_305
	s_movk_i32 s51, 0x2000
	s_mov_b32 s73, 0x10000
	s_mov_b32 s75, 0x12000
	s_and_b64 vcc, exec, s[16:17]
	s_cbranch_vccz .LBB0_308

.LBB0_530:
	s_add_u32 vcc_lo, s14, 0xfff80000
	s_addc_u32 vcc_hi, s15, -1
	v_lshl_add_u64 v[192:193], vcc, 0, v[138:139]
	s_mov_b32 m0, s27
	s_nop 0
	global_load_lds_dwordx4 v[192:193], off
	v_lshl_add_u64 v[192:193], vcc, 0, v[140:141]
	s_mov_b32 m0, s28
	s_nop 0
	global_load_lds_dwordx4 v[192:193], off
	ds_read_b128 v[152:155], v145
	ds_read_b128 v[156:159], v145 offset:1024
	ds_read_b128 v[160:163], v145 offset:2048
	ds_read_b128 v[164:167], v145 offset:3072
	ds_read_b128 v[168:171], v145 offset:16384
	ds_read_b128 v[172:175], v145 offset:17408
	ds_read_b128 v[176:179], v145 offset:18432
	ds_read_b128 v[180:183], v145 offset:19456
	ds_read_b128 v[184:187], v151
	ds_read_b128 v[188:191], v151 offset:1024
	ds_read_b128 v[204:207], v151 offset:2048
	ds_read_b128 v[208:211], v151 offset:3072
	ds_read_b128 v[212:215], v151 offset:4096
	ds_read_b128 v[216:219], v151 offset:5120
	ds_read_b128 v[220:223], v151 offset:6144
	ds_read_b128 v[224:227], v151 offset:7168
	s_add_u32 s16, s14, 0xfff80080
	s_addc_u32 s17, s15, -1
	s_add_i32 s40, 0, 0x10000
	s_cmp_eq_u32 s39, 28
	s_cselect_b32 s19, s34, s17
	s_cselect_b32 s18, s35, s16
	s_cselect_b32 s17, s9, s38
	s_cselect_b32 s16, s36, s37
	s_add_i32 s42, 0, 0x14000
	v_lshl_add_u64 v[192:193], s[14:15], 0, v[138:139]
	s_add_i32 m0, s23, 0xc000
	s_nop 0
	global_load_lds_dwordx4 v[192:193], off
	v_lshl_add_u64 v[192:193], s[14:15], 0, v[140:141]
	s_add_i32 m0, s23, 0xe000
	s_nop 0
	global_load_lds_dwordx4 v[192:193], off
	s_waitcnt vmcnt(8)
	s_waitcnt lgkmcnt(0)
	v_mfma_f32_16x16x32_bf16 v[126:129], v[152:155], v[184:187], v[126:129]
	v_mfma_f32_16x16x32_bf16 v[126:129], v[156:159], v[188:191], v[126:129]
	s_barrier
	s_setprio 1
	v_mfma_f32_16x16x32_bf16 v[122:125], v[164:167], v[188:191], v[122:125]
	v_mfma_f32_16x16x32_bf16 v[122:125], v[160:163], v[184:187], v[122:125]
	v_mfma_f32_16x16x32_bf16 v[106:109], v[160:163], v[204:207], v[106:109]
	v_mfma_f32_16x16x32_bf16 v[106:109], v[164:167], v[208:211], v[106:109]
	v_mfma_f32_16x16x32_bf16 v[110:113], v[156:159], v[208:211], v[110:113]
	v_mfma_f32_16x16x32_bf16 v[110:113], v[152:155], v[204:207], v[110:113]
	v_mfma_f32_16x16x32_bf16 v[94:97], v[152:155], v[212:215], v[94:97]
	v_mfma_f32_16x16x32_bf16 v[94:97], v[156:159], v[216:219], v[94:97]
	v_mfma_f32_16x16x32_bf16 v[90:93], v[164:167], v[216:219], v[90:93]
	v_mfma_f32_16x16x32_bf16 v[90:93], v[160:163], v[212:215], v[90:93]
	v_mfma_f32_16x16x32_bf16 v[74:77], v[160:163], v[220:223], v[74:77]
	v_mfma_f32_16x16x32_bf16 v[74:77], v[164:167], v[224:227], v[74:77]
	v_mfma_f32_16x16x32_bf16 v[78:81], v[156:159], v[224:227], v[78:81]
	v_mfma_f32_16x16x32_bf16 v[78:81], v[152:155], v[220:223], v[78:81]
	v_mfma_f32_16x16x32_bf16 v[118:121], v[168:171], v[184:187], v[118:121]
	v_mfma_f32_16x16x32_bf16 v[118:121], v[172:175], v[188:191], v[118:121]
	v_mfma_f32_16x16x32_bf16 v[114:117], v[180:183], v[188:191], v[114:117]
	v_mfma_f32_16x16x32_bf16 v[114:117], v[176:179], v[184:187], v[114:117]
	v_mfma_f32_16x16x32_bf16 v[98:101], v[176:179], v[204:207], v[98:101]
	v_mfma_f32_16x16x32_bf16 v[98:101], v[180:183], v[208:211], v[98:101]
	v_mfma_f32_16x16x32_bf16 v[102:105], v[172:175], v[208:211], v[102:105]
	v_mfma_f32_16x16x32_bf16 v[102:105], v[168:171], v[204:207], v[102:105]
	v_mfma_f32_16x16x32_bf16 v[86:89], v[168:171], v[212:215], v[86:89]
	v_mfma_f32_16x16x32_bf16 v[86:89], v[172:175], v[216:219], v[86:89]
	v_mfma_f32_16x16x32_bf16 v[82:85], v[180:183], v[216:219], v[82:85]
	v_mfma_f32_16x16x32_bf16 v[82:85], v[176:179], v[212:215], v[82:85]
	v_mfma_f32_16x16x32_bf16 v[66:69], v[176:179], v[220:223], v[66:69]
	v_mfma_f32_16x16x32_bf16 v[66:69], v[180:183], v[224:227], v[66:69]
	v_mfma_f32_16x16x32_bf16 v[70:73], v[172:175], v[224:227], v[70:73]
	v_mfma_f32_16x16x32_bf16 v[70:73], v[168:171], v[220:223], v[70:73]
	s_setprio 0
	s_barrier
	ds_read_b128 v[184:187], v151 offset:16384
	ds_read_b128 v[188:191], v151 offset:17408
	ds_read_b128 v[204:207], v151 offset:18432
	ds_read_b128 v[208:211], v151 offset:19456
	ds_read_b128 v[212:215], v151 offset:20480
	ds_read_b128 v[216:219], v151 offset:21504
	ds_read_b128 v[220:223], v151 offset:22528
	ds_read_b128 v[224:227], v151 offset:23552
	s_add_i32 s40, s40, s22
	v_lshl_add_u64 v[192:193], s[16:17], 0, v[134:135]
	s_mov_b32 m0, s40
	s_nop 0
	global_load_lds_dwordx4 v[192:193], off
	s_add_i32 m0, s40, 0x2000
	s_add_u32 s40, s16, 0x80000
	v_lshl_add_u64 v[198:199], s[16:17], 0, v[130:131]
	s_addc_u32 s41, s17, 0
	s_add_i32 s42, s42, s22
	global_load_lds_dwordx4 v[198:199], off
	v_lshl_add_u64 v[228:229], s[40:41], 0, v[134:135]
	s_mov_b32 m0, s42
	v_lshl_add_u64 v[230:231], s[18:19], 0, v[132:133]
	global_load_lds_dwordx4 v[228:229], off
	v_lshl_add_u64 v[228:229], s[40:41], 0, v[130:131]
	s_add_i32 m0, s42, 0x2000
	s_nop 0
	global_load_lds_dwordx4 v[228:229], off
	v_lshl_add_u64 v[228:229], s[18:19], 0, v[136:137]
	s_waitcnt vmcnt(6)
	s_waitcnt lgkmcnt(0)
	v_mfma_f32_16x16x32_bf16 v[62:65], v[152:155], v[184:187], v[62:65]
	v_mfma_f32_16x16x32_bf16 v[62:65], v[156:159], v[188:191], v[62:65]
	s_barrier
	s_setprio 1
	v_mfma_f32_16x16x32_bf16 v[58:61], v[164:167], v[188:191], v[58:61]
	v_mfma_f32_16x16x32_bf16 v[58:61], v[160:163], v[184:187], v[58:61]
	v_mfma_f32_16x16x32_bf16 v[42:45], v[160:163], v[204:207], v[42:45]
	v_mfma_f32_16x16x32_bf16 v[42:45], v[164:167], v[208:211], v[42:45]
	v_mfma_f32_16x16x32_bf16 v[46:49], v[156:159], v[208:211], v[46:49]
	v_mfma_f32_16x16x32_bf16 v[46:49], v[152:155], v[204:207], v[46:49]
	v_mfma_f32_16x16x32_bf16 v[30:33], v[152:155], v[212:215], v[30:33]
	v_mfma_f32_16x16x32_bf16 v[30:33], v[156:159], v[216:219], v[30:33]
	v_mfma_f32_16x16x32_bf16 v[26:29], v[164:167], v[216:219], v[26:29]
	v_mfma_f32_16x16x32_bf16 v[26:29], v[160:163], v[212:215], v[26:29]
	v_mfma_f32_16x16x32_bf16 v[10:13], v[160:163], v[220:223], v[10:13]
	v_mfma_f32_16x16x32_bf16 v[10:13], v[164:167], v[224:227], v[10:13]
	v_mfma_f32_16x16x32_bf16 v[14:17], v[156:159], v[224:227], v[14:17]
	v_mfma_f32_16x16x32_bf16 v[14:17], v[152:155], v[220:223], v[14:17]
	v_mfma_f32_16x16x32_bf16 v[54:57], v[168:171], v[184:187], v[54:57]
	v_mfma_f32_16x16x32_bf16 v[54:57], v[172:175], v[188:191], v[54:57]
	v_mfma_f32_16x16x32_bf16 v[50:53], v[180:183], v[188:191], v[50:53]
	v_mfma_f32_16x16x32_bf16 v[50:53], v[176:179], v[184:187], v[50:53]
	v_mfma_f32_16x16x32_bf16 v[34:37], v[176:179], v[204:207], v[34:37]
	v_mfma_f32_16x16x32_bf16 v[34:37], v[180:183], v[208:211], v[34:37]
	v_mfma_f32_16x16x32_bf16 v[38:41], v[172:175], v[208:211], v[38:41]
	v_mfma_f32_16x16x32_bf16 v[38:41], v[168:171], v[204:207], v[38:41]
	v_mfma_f32_16x16x32_bf16 v[22:25], v[168:171], v[212:215], v[22:25]
	v_mfma_f32_16x16x32_bf16 v[22:25], v[172:175], v[216:219], v[22:25]
	v_mfma_f32_16x16x32_bf16 v[18:21], v[180:183], v[216:219], v[18:21]
	v_mfma_f32_16x16x32_bf16 v[18:21], v[176:179], v[212:215], v[18:21]
	v_mfma_f32_16x16x32_bf16 v[2:5], v[176:179], v[220:223], v[2:5]
	v_mfma_f32_16x16x32_bf16 v[2:5], v[180:183], v[224:227], v[2:5]
	v_mfma_f32_16x16x32_bf16 v[6:9], v[172:175], v[224:227], v[6:9]
	v_mfma_f32_16x16x32_bf16 v[6:9], v[168:171], v[220:223], v[6:9]
	s_setprio 0
	s_barrier
	s_mov_b32 m0, s23
	s_nop 0
	global_load_lds_dwordx4 v[228:229], off
	s_mov_b32 m0, s24
	s_nop 0
	global_load_lds_dwordx4 v[230:231], off
	ds_read_b128 v[152:155], v145 offset:32768
	ds_read_b128 v[156:159], v145 offset:33792
	ds_read_b128 v[160:163], v145 offset:34816
	ds_read_b128 v[164:167], v145 offset:35840
	ds_read_b128 v[168:171], v145 offset:49152
	ds_read_b128 v[172:175], v145 offset:50176
	ds_read_b128 v[176:179], v145 offset:51200
	ds_read_b128 v[180:183], v145 offset:52224
	ds_read_b128 v[184:187], v151 offset:32768
	ds_read_b128 v[188:191], v151 offset:33792
	ds_read_b128 v[204:207], v151 offset:34816
	ds_read_b128 v[208:211], v151 offset:35840
	ds_read_b128 v[212:215], v151 offset:36864
	ds_read_b128 v[216:219], v151 offset:37888
	ds_read_b128 v[220:223], v151 offset:38912
	ds_read_b128 v[224:227], v151 offset:39936
	s_add_i32 s40, 0, 0x18000
	s_add_i32 s41, 0, 0x1c000
	s_add_u32 s18, s18, 0x80000
	s_addc_u32 s19, s19, 0
	s_mov_b32 m0, s25
	v_lshl_add_u64 v[232:233], s[18:19], 0, v[136:137]
	global_load_lds_dwordx4 v[232:233], off
	v_lshl_add_u64 v[232:233], s[18:19], 0, v[132:133]
	s_mov_b32 m0, s26
	s_nop 0
	global_load_lds_dwordx4 v[232:233], off
	s_waitcnt vmcnt(8)
	s_waitcnt lgkmcnt(0)
	v_mfma_f32_16x16x32_bf16 v[126:129], v[152:155], v[184:187], v[126:129]
	v_mfma_f32_16x16x32_bf16 v[126:129], v[156:159], v[188:191], v[126:129]
	s_barrier
	s_setprio 1
	v_mfma_f32_16x16x32_bf16 v[122:125], v[164:167], v[188:191], v[122:125]
	v_mfma_f32_16x16x32_bf16 v[122:125], v[160:163], v[184:187], v[122:125]
	v_mfma_f32_16x16x32_bf16 v[106:109], v[160:163], v[204:207], v[106:109]
	v_mfma_f32_16x16x32_bf16 v[106:109], v[164:167], v[208:211], v[106:109]
	v_mfma_f32_16x16x32_bf16 v[110:113], v[156:159], v[208:211], v[110:113]
	v_mfma_f32_16x16x32_bf16 v[110:113], v[152:155], v[204:207], v[110:113]
	v_mfma_f32_16x16x32_bf16 v[94:97], v[152:155], v[212:215], v[94:97]
	v_mfma_f32_16x16x32_bf16 v[94:97], v[156:159], v[216:219], v[94:97]
	v_mfma_f32_16x16x32_bf16 v[90:93], v[164:167], v[216:219], v[90:93]
	v_mfma_f32_16x16x32_bf16 v[90:93], v[160:163], v[212:215], v[90:93]
	v_mfma_f32_16x16x32_bf16 v[74:77], v[160:163], v[220:223], v[74:77]
	v_mfma_f32_16x16x32_bf16 v[74:77], v[164:167], v[224:227], v[74:77]
	v_mfma_f32_16x16x32_bf16 v[78:81], v[156:159], v[224:227], v[78:81]
	v_mfma_f32_16x16x32_bf16 v[78:81], v[152:155], v[220:223], v[78:81]
	v_mfma_f32_16x16x32_bf16 v[118:121], v[168:171], v[184:187], v[118:121]
	v_mfma_f32_16x16x32_bf16 v[118:121], v[172:175], v[188:191], v[118:121]
	v_mfma_f32_16x16x32_bf16 v[114:117], v[180:183], v[188:191], v[114:117]
	v_mfma_f32_16x16x32_bf16 v[114:117], v[176:179], v[184:187], v[114:117]
	v_mfma_f32_16x16x32_bf16 v[98:101], v[176:179], v[204:207], v[98:101]
	v_mfma_f32_16x16x32_bf16 v[98:101], v[180:183], v[208:211], v[98:101]
	v_mfma_f32_16x16x32_bf16 v[102:105], v[172:175], v[208:211], v[102:105]
	v_mfma_f32_16x16x32_bf16 v[102:105], v[168:171], v[204:207], v[102:105]
	v_mfma_f32_16x16x32_bf16 v[86:89], v[168:171], v[212:215], v[86:89]
	v_mfma_f32_16x16x32_bf16 v[86:89], v[172:175], v[216:219], v[86:89]
	v_mfma_f32_16x16x32_bf16 v[82:85], v[180:183], v[216:219], v[82:85]
	v_mfma_f32_16x16x32_bf16 v[82:85], v[176:179], v[212:215], v[82:85]
	v_mfma_f32_16x16x32_bf16 v[66:69], v[176:179], v[220:223], v[66:69]
	v_mfma_f32_16x16x32_bf16 v[66:69], v[180:183], v[224:227], v[66:69]
	v_mfma_f32_16x16x32_bf16 v[70:73], v[172:175], v[224:227], v[70:73]
	v_mfma_f32_16x16x32_bf16 v[70:73], v[168:171], v[220:223], v[70:73]
	s_setprio 0
	s_barrier
	ds_read_b128 v[184:187], v151 offset:49152
	ds_read_b128 v[188:191], v151 offset:50176
	ds_read_b128 v[204:207], v151 offset:51200
	ds_read_b128 v[208:211], v151 offset:52224
	ds_read_b128 v[212:215], v151 offset:53248
	ds_read_b128 v[216:219], v151 offset:54272
	ds_read_b128 v[220:223], v151 offset:55296
	ds_read_b128 v[224:227], v151 offset:56320
	s_add_i32 s18, s40, s22
	v_lshl_add_u64 v[192:193], v[192:193], 0, s[94:95]
	s_mov_b32 m0, s18
	s_nop 0
	global_load_lds_dwordx4 v[192:193], off
	s_add_i32 m0, s18, 0x2000
	s_add_u32 s16, s16, 0x80080
	v_lshl_add_u64 v[192:193], v[198:199], 0, s[94:95]
	s_addc_u32 s17, s17, 0
	s_add_i32 s18, s41, s22
	global_load_lds_dwordx4 v[192:193], off
	v_lshl_add_u64 v[192:193], s[16:17], 0, v[134:135]
	s_mov_b32 m0, s18
	s_nop 0
	global_load_lds_dwordx4 v[192:193], off
	v_lshl_add_u64 v[192:193], s[16:17], 0, v[130:131]
	s_add_i32 m0, s18, 0x2000
	s_nop 0
	global_load_lds_dwordx4 v[192:193], off
	s_waitcnt vmcnt(6)
	s_waitcnt lgkmcnt(0)
	v_mfma_f32_16x16x32_bf16 v[62:65], v[152:155], v[184:187], v[62:65]
	v_mfma_f32_16x16x32_bf16 v[62:65], v[156:159], v[188:191], v[62:65]
	s_barrier
	s_setprio 1
	v_mfma_f32_16x16x32_bf16 v[58:61], v[164:167], v[188:191], v[58:61]
	v_mfma_f32_16x16x32_bf16 v[58:61], v[160:163], v[184:187], v[58:61]
	v_mfma_f32_16x16x32_bf16 v[42:45], v[160:163], v[204:207], v[42:45]
	v_mfma_f32_16x16x32_bf16 v[42:45], v[164:167], v[208:211], v[42:45]
	v_mfma_f32_16x16x32_bf16 v[46:49], v[156:159], v[208:211], v[46:49]
	v_mfma_f32_16x16x32_bf16 v[46:49], v[152:155], v[204:207], v[46:49]
	v_mfma_f32_16x16x32_bf16 v[30:33], v[152:155], v[212:215], v[30:33]
	v_mfma_f32_16x16x32_bf16 v[30:33], v[156:159], v[216:219], v[30:33]
	v_mfma_f32_16x16x32_bf16 v[26:29], v[164:167], v[216:219], v[26:29]
	v_mfma_f32_16x16x32_bf16 v[26:29], v[160:163], v[212:215], v[26:29]
	v_mfma_f32_16x16x32_bf16 v[10:13], v[160:163], v[220:223], v[10:13]
	v_mfma_f32_16x16x32_bf16 v[10:13], v[164:167], v[224:227], v[10:13]
	s_add_i32 s39, s39, 2
	v_mfma_f32_16x16x32_bf16 v[14:17], v[156:159], v[224:227], v[14:17]
	v_mfma_f32_16x16x32_bf16 v[14:17], v[152:155], v[220:223], v[14:17]
	s_add_u32 s14, s14, 0x100
	v_mfma_f32_16x16x32_bf16 v[54:57], v[168:171], v[184:187], v[54:57]
	v_mfma_f32_16x16x32_bf16 v[54:57], v[172:175], v[188:191], v[54:57]
	s_addc_u32 s15, s15, 0
	v_mfma_f32_16x16x32_bf16 v[50:53], v[180:183], v[188:191], v[50:53]
	v_mfma_f32_16x16x32_bf16 v[50:53], v[176:179], v[184:187], v[50:53]
	s_add_u32 s37, s37, 0x100
	v_mfma_f32_16x16x32_bf16 v[34:37], v[176:179], v[204:207], v[34:37]
	v_mfma_f32_16x16x32_bf16 v[34:37], v[180:183], v[208:211], v[34:37]
	s_addc_u32 s38, s38, 0
	v_mfma_f32_16x16x32_bf16 v[38:41], v[172:175], v[208:211], v[38:41]
	v_mfma_f32_16x16x32_bf16 v[38:41], v[168:171], v[204:207], v[38:41]
	s_cmp_gt_u32 s39, 29
	v_mfma_f32_16x16x32_bf16 v[22:25], v[168:171], v[212:215], v[22:25]
	v_mfma_f32_16x16x32_bf16 v[22:25], v[172:175], v[216:219], v[22:25]
	v_mfma_f32_16x16x32_bf16 v[18:21], v[180:183], v[216:219], v[18:21]
	v_mfma_f32_16x16x32_bf16 v[18:21], v[176:179], v[212:215], v[18:21]
	v_mfma_f32_16x16x32_bf16 v[2:5], v[176:179], v[220:223], v[2:5]
	v_mfma_f32_16x16x32_bf16 v[2:5], v[180:183], v[224:227], v[2:5]
	v_mfma_f32_16x16x32_bf16 v[6:9], v[172:175], v[224:227], v[6:9]
	v_mfma_f32_16x16x32_bf16 v[6:9], v[168:171], v[220:223], v[6:9]
	s_setprio 0
	s_barrier
	s_cbranch_scc0 .LBB0_530
	s_and_b64 vcc, exec, s[6:7]
	s_cbranch_vccz .LBB0_533
	s_barrier

.LBB0_850:
	s_sub_u32 vcc_lo, s18, s12
	s_subb_u32 vcc_hi, s19, 0
	v_lshl_add_u64 v[214:215], vcc, 0, v[210:211]
	s_mov_b32 m0, s33
	s_nop 0
	global_load_lds_dwordx4 v[214:215], off
	v_lshl_add_u64 v[214:215], vcc, 0, v[212:213]
	s_mov_b32 m0, s34
	s_nop 0
	global_load_lds_dwordx4 v[214:215], off
	ds_read_b128 v[66:69], v198
	ds_read_b128 v[78:81], v198 offset:1024
	ds_read_b128 v[82:85], v198 offset:2048
	ds_read_b128 v[98:101], v198 offset:3072
	ds_read_b128 v[106:109], v198 offset:16384
	ds_read_b128 v[118:121], v198 offset:17408
	ds_read_b128 v[130:133], v198 offset:18432
	ds_read_b128 v[142:145], v198 offset:19456
	ds_read_b128 v[150:153], v234
	ds_read_b128 v[154:157], v234 offset:1024
	ds_read_b128 v[158:161], v234 offset:2048
	ds_read_b128 v[162:165], v234 offset:3072
	ds_read_b128 v[170:173], v234 offset:4096
	ds_read_b128 v[174:177], v234 offset:5120
	ds_read_b128 v[178:181], v234 offset:6144
	ds_read_b128 v[190:193], v234 offset:7168
	s_add_i32 s55, s20, 2
	s_add_u32 s56, s18, 0x80
	s_addc_u32 s21, s19, 0
	s_add_i32 s58, 0, 0x10000
	s_cmp_eq_u32 s35, s20
	s_cselect_b32 s21, s1, s21
	s_cselect_b32 s20, s0, s56
	s_cselect_b32 s57, s17, s54
	s_cselect_b32 s56, s16, s51
	s_add_i32 s59, 0, 0x14000
	v_lshl_add_u64 v[214:215], s[18:19], 0, v[210:211]
	s_add_i32 m0, s26, 0xc000
	s_nop 0
	global_load_lds_dwordx4 v[214:215], off
	v_lshl_add_u64 v[214:215], s[18:19], 0, v[212:213]
	s_add_i32 m0, s26, 0xe000
	s_nop 0
	global_load_lds_dwordx4 v[214:215], off
	s_waitcnt vmcnt(8)
	s_waitcnt lgkmcnt(0)
	v_mfma_f32_16x16x32_bf16 v[186:189], v[66:69], v[150:153], v[186:189]
	v_mfma_f32_16x16x32_bf16 v[186:189], v[78:81], v[154:157], v[186:189]
	s_barrier
	s_setprio 1
	v_mfma_f32_16x16x32_bf16 v[182:185], v[98:101], v[154:157], v[182:185]
	v_mfma_f32_16x16x32_bf16 v[182:185], v[82:85], v[150:153], v[182:185]
	v_mfma_f32_16x16x32_bf16 v[134:137], v[82:85], v[158:161], v[134:137]
	v_mfma_f32_16x16x32_bf16 v[134:137], v[98:101], v[162:165], v[134:137]
	v_mfma_f32_16x16x32_bf16 v[138:141], v[78:81], v[162:165], v[138:141]
	v_mfma_f32_16x16x32_bf16 v[138:141], v[66:69], v[158:161], v[138:141]
	v_mfma_f32_16x16x32_bf16 v[114:117], v[66:69], v[170:173], v[114:117]
	v_mfma_f32_16x16x32_bf16 v[114:117], v[78:81], v[174:177], v[114:117]
	v_mfma_f32_16x16x32_bf16 v[110:113], v[98:101], v[174:177], v[110:113]
	v_mfma_f32_16x16x32_bf16 v[110:113], v[82:85], v[170:173], v[110:113]
	v_mfma_f32_16x16x32_bf16 v[86:89], v[82:85], v[178:181], v[86:89]
	v_mfma_f32_16x16x32_bf16 v[86:89], v[98:101], v[190:193], v[86:89]
	v_mfma_f32_16x16x32_bf16 v[90:93], v[78:81], v[190:193], v[90:93]
	v_mfma_f32_16x16x32_bf16 v[90:93], v[66:69], v[178:181], v[90:93]
	v_mfma_f32_16x16x32_bf16 v[166:169], v[106:109], v[150:153], v[166:169]
	v_mfma_f32_16x16x32_bf16 v[166:169], v[118:121], v[154:157], v[166:169]
	v_mfma_f32_16x16x32_bf16 v[146:149], v[142:145], v[154:157], v[146:149]
	v_mfma_f32_16x16x32_bf16 v[146:149], v[130:133], v[150:153], v[146:149]
	v_mfma_f32_16x16x32_bf16 v[122:125], v[130:133], v[158:161], v[122:125]
	v_mfma_f32_16x16x32_bf16 v[122:125], v[142:145], v[162:165], v[122:125]
	v_mfma_f32_16x16x32_bf16 v[126:129], v[118:121], v[162:165], v[126:129]
	v_mfma_f32_16x16x32_bf16 v[126:129], v[106:109], v[158:161], v[126:129]
	v_mfma_f32_16x16x32_bf16 v[102:105], v[106:109], v[170:173], v[102:105]
	v_mfma_f32_16x16x32_bf16 v[102:105], v[118:121], v[174:177], v[102:105]
	v_mfma_f32_16x16x32_bf16 v[94:97], v[142:145], v[174:177], v[94:97]
	v_mfma_f32_16x16x32_bf16 v[94:97], v[130:133], v[170:173], v[94:97]
	v_mfma_f32_16x16x32_bf16 v[70:73], v[130:133], v[178:181], v[70:73]
	v_mfma_f32_16x16x32_bf16 v[70:73], v[142:145], v[190:193], v[70:73]
	v_mfma_f32_16x16x32_bf16 v[74:77], v[118:121], v[190:193], v[74:77]
	v_mfma_f32_16x16x32_bf16 v[74:77], v[106:109], v[178:181], v[74:77]
	s_setprio 0
	s_barrier
	ds_read_b128 v[150:153], v234 offset:16384
	ds_read_b128 v[154:157], v234 offset:17408
	ds_read_b128 v[158:161], v234 offset:18432
	ds_read_b128 v[162:165], v234 offset:19456
	ds_read_b128 v[170:173], v234 offset:20480
	ds_read_b128 v[174:177], v234 offset:21504
	ds_read_b128 v[178:181], v234 offset:22528
	ds_read_b128 v[190:193], v234 offset:23552
	s_add_i32 s58, s58, s24
	v_lshl_add_u64 v[214:215], s[56:57], 0, v[194:195]
	s_mov_b32 m0, s58
	s_nop 0
	global_load_lds_dwordx4 v[214:215], off
	s_add_i32 m0, s58, 0x2000
	v_lshl_add_u64 v[216:217], s[56:57], 0, v[204:205]
	s_add_u32 s56, s56, s12
	s_addc_u32 s57, s57, 0
	s_add_i32 s58, s59, s24
	global_load_lds_dwordx4 v[216:217], off
	v_lshl_add_u64 v[218:219], s[56:57], 0, v[194:195]
	s_mov_b32 m0, s58
	v_lshl_add_u64 v[220:221], s[56:57], 0, v[204:205]
	global_load_lds_dwordx4 v[218:219], off
	s_add_i32 m0, s58, 0x2000
	v_lshl_add_u64 v[222:223], s[20:21], 0, v[208:209]
	global_load_lds_dwordx4 v[220:221], off
	v_lshl_add_u64 v[224:225], s[20:21], 0, v[206:207]
	s_waitcnt vmcnt(6)
	s_waitcnt lgkmcnt(0)
	v_mfma_f32_16x16x32_bf16 v[62:65], v[66:69], v[150:153], v[62:65]
	v_mfma_f32_16x16x32_bf16 v[62:65], v[78:81], v[154:157], v[62:65]
	s_barrier
	s_setprio 1
	v_mfma_f32_16x16x32_bf16 v[58:61], v[98:101], v[154:157], v[58:61]
	v_mfma_f32_16x16x32_bf16 v[58:61], v[82:85], v[150:153], v[58:61]
	v_mfma_f32_16x16x32_bf16 v[42:45], v[82:85], v[158:161], v[42:45]
	v_mfma_f32_16x16x32_bf16 v[42:45], v[98:101], v[162:165], v[42:45]
	v_mfma_f32_16x16x32_bf16 v[46:49], v[78:81], v[162:165], v[46:49]
	v_mfma_f32_16x16x32_bf16 v[46:49], v[66:69], v[158:161], v[46:49]
	v_mfma_f32_16x16x32_bf16 v[30:33], v[66:69], v[170:173], v[30:33]
	v_mfma_f32_16x16x32_bf16 v[30:33], v[78:81], v[174:177], v[30:33]
	v_mfma_f32_16x16x32_bf16 v[26:29], v[98:101], v[174:177], v[26:29]
	v_mfma_f32_16x16x32_bf16 v[26:29], v[82:85], v[170:173], v[26:29]
	v_mfma_f32_16x16x32_bf16 v[10:13], v[82:85], v[178:181], v[10:13]
	v_mfma_f32_16x16x32_bf16 v[10:13], v[98:101], v[190:193], v[10:13]
	v_mfma_f32_16x16x32_bf16 v[14:17], v[78:81], v[190:193], v[14:17]
	v_mfma_f32_16x16x32_bf16 v[14:17], v[66:69], v[178:181], v[14:17]
	v_mfma_f32_16x16x32_bf16 v[54:57], v[106:109], v[150:153], v[54:57]
	v_mfma_f32_16x16x32_bf16 v[54:57], v[118:121], v[154:157], v[54:57]
	v_mfma_f32_16x16x32_bf16 v[50:53], v[142:145], v[154:157], v[50:53]
	v_mfma_f32_16x16x32_bf16 v[50:53], v[130:133], v[150:153], v[50:53]
	v_mfma_f32_16x16x32_bf16 v[34:37], v[130:133], v[158:161], v[34:37]
	v_mfma_f32_16x16x32_bf16 v[34:37], v[142:145], v[162:165], v[34:37]
	v_mfma_f32_16x16x32_bf16 v[38:41], v[118:121], v[162:165], v[38:41]
	v_mfma_f32_16x16x32_bf16 v[38:41], v[106:109], v[158:161], v[38:41]
	v_mfma_f32_16x16x32_bf16 v[22:25], v[106:109], v[170:173], v[22:25]
	v_mfma_f32_16x16x32_bf16 v[22:25], v[118:121], v[174:177], v[22:25]
	v_mfma_f32_16x16x32_bf16 v[18:21], v[142:145], v[174:177], v[18:21]
	v_mfma_f32_16x16x32_bf16 v[18:21], v[130:133], v[170:173], v[18:21]
	v_mfma_f32_16x16x32_bf16 v[2:5], v[130:133], v[178:181], v[2:5]
	v_mfma_f32_16x16x32_bf16 v[2:5], v[142:145], v[190:193], v[2:5]
	v_mfma_f32_16x16x32_bf16 v[6:9], v[118:121], v[190:193], v[6:9]
	v_mfma_f32_16x16x32_bf16 v[6:9], v[106:109], v[178:181], v[6:9]
	s_setprio 0
	s_barrier
	s_mov_b32 m0, s26
	s_nop 0
	global_load_lds_dwordx4 v[222:223], off
	s_mov_b32 m0, s27
	s_nop 0
	global_load_lds_dwordx4 v[224:225], off
	ds_read_b128 v[66:69], v198 offset:32768
	ds_read_b128 v[78:81], v198 offset:33792
	ds_read_b128 v[82:85], v198 offset:34816
	ds_read_b128 v[98:101], v198 offset:35840
	ds_read_b128 v[106:109], v198 offset:49152
	ds_read_b128 v[118:121], v198 offset:50176
	ds_read_b128 v[130:133], v198 offset:51200
	ds_read_b128 v[142:145], v198 offset:52224
	ds_read_b128 v[150:153], v234 offset:32768
	ds_read_b128 v[154:157], v234 offset:33792
	ds_read_b128 v[158:161], v234 offset:34816
	ds_read_b128 v[162:165], v234 offset:35840
	ds_read_b128 v[170:173], v234 offset:36864
	ds_read_b128 v[174:177], v234 offset:37888
	ds_read_b128 v[178:181], v234 offset:38912
	ds_read_b128 v[190:193], v234 offset:39936
	s_add_i32 s56, 0, 0x18000
	s_add_i32 s57, 0, 0x1c000
	s_add_u32 s20, s20, s12
	s_addc_u32 s21, s21, 0
	s_mov_b32 m0, s28
	v_lshl_add_u64 v[226:227], s[20:21], 0, v[208:209]
	global_load_lds_dwordx4 v[226:227], off
	v_lshl_add_u64 v[226:227], s[20:21], 0, v[206:207]
	s_mov_b32 m0, s29
	s_nop 0
	global_load_lds_dwordx4 v[226:227], off
	s_waitcnt vmcnt(8)
	s_waitcnt lgkmcnt(0)
	v_mfma_f32_16x16x32_bf16 v[186:189], v[66:69], v[150:153], v[186:189]
	v_mfma_f32_16x16x32_bf16 v[186:189], v[78:81], v[154:157], v[186:189]
	s_barrier
	s_setprio 1
	v_mfma_f32_16x16x32_bf16 v[182:185], v[98:101], v[154:157], v[182:185]
	v_mfma_f32_16x16x32_bf16 v[182:185], v[82:85], v[150:153], v[182:185]
	v_mfma_f32_16x16x32_bf16 v[134:137], v[82:85], v[158:161], v[134:137]
	v_mfma_f32_16x16x32_bf16 v[134:137], v[98:101], v[162:165], v[134:137]
	v_mfma_f32_16x16x32_bf16 v[138:141], v[78:81], v[162:165], v[138:141]
	v_mfma_f32_16x16x32_bf16 v[138:141], v[66:69], v[158:161], v[138:141]
	v_mfma_f32_16x16x32_bf16 v[114:117], v[66:69], v[170:173], v[114:117]
	v_mfma_f32_16x16x32_bf16 v[114:117], v[78:81], v[174:177], v[114:117]
	v_mfma_f32_16x16x32_bf16 v[110:113], v[98:101], v[174:177], v[110:113]
	v_mfma_f32_16x16x32_bf16 v[110:113], v[82:85], v[170:173], v[110:113]
	v_mfma_f32_16x16x32_bf16 v[86:89], v[82:85], v[178:181], v[86:89]
	v_mfma_f32_16x16x32_bf16 v[86:89], v[98:101], v[190:193], v[86:89]
	v_mfma_f32_16x16x32_bf16 v[90:93], v[78:81], v[190:193], v[90:93]
	v_mfma_f32_16x16x32_bf16 v[90:93], v[66:69], v[178:181], v[90:93]
	v_mfma_f32_16x16x32_bf16 v[166:169], v[106:109], v[150:153], v[166:169]
	v_mfma_f32_16x16x32_bf16 v[166:169], v[118:121], v[154:157], v[166:169]
	v_mfma_f32_16x16x32_bf16 v[146:149], v[142:145], v[154:157], v[146:149]
	v_mfma_f32_16x16x32_bf16 v[146:149], v[130:133], v[150:153], v[146:149]
	v_mfma_f32_16x16x32_bf16 v[122:125], v[130:133], v[158:161], v[122:125]
	v_mfma_f32_16x16x32_bf16 v[122:125], v[142:145], v[162:165], v[122:125]
	v_mfma_f32_16x16x32_bf16 v[126:129], v[118:121], v[162:165], v[126:129]
	v_mfma_f32_16x16x32_bf16 v[126:129], v[106:109], v[158:161], v[126:129]
	v_mfma_f32_16x16x32_bf16 v[102:105], v[106:109], v[170:173], v[102:105]
	v_mfma_f32_16x16x32_bf16 v[102:105], v[118:121], v[174:177], v[102:105]
	v_mfma_f32_16x16x32_bf16 v[94:97], v[142:145], v[174:177], v[94:97]
	v_mfma_f32_16x16x32_bf16 v[94:97], v[130:133], v[170:173], v[94:97]
	v_mfma_f32_16x16x32_bf16 v[70:73], v[130:133], v[178:181], v[70:73]
	v_mfma_f32_16x16x32_bf16 v[70:73], v[142:145], v[190:193], v[70:73]
	v_mfma_f32_16x16x32_bf16 v[74:77], v[118:121], v[190:193], v[74:77]
	v_mfma_f32_16x16x32_bf16 v[74:77], v[106:109], v[178:181], v[74:77]
	s_setprio 0
	s_barrier
	ds_read_b128 v[150:153], v234 offset:49152
	ds_read_b128 v[154:157], v234 offset:50176
	ds_read_b128 v[158:161], v234 offset:51200
	ds_read_b128 v[162:165], v234 offset:52224
	ds_read_b128 v[170:173], v234 offset:53248
	ds_read_b128 v[174:177], v234 offset:54272
	ds_read_b128 v[178:181], v234 offset:55296
	ds_read_b128 v[190:193], v234 offset:56320
	s_add_i32 s20, s56, s24
	v_lshl_add_u64 v[214:215], v[214:215], 0, s[94:95]
	s_mov_b32 m0, s20
	s_nop 0
	global_load_lds_dwordx4 v[214:215], off
	v_lshl_add_u64 v[214:215], v[216:217], 0, s[94:95]
	s_add_i32 m0, s20, 0x2000
	s_add_i32 s20, s57, s24
	global_load_lds_dwordx4 v[214:215], off
	v_lshl_add_u64 v[214:215], v[218:219], 0, s[94:95]
	s_mov_b32 m0, s20
	s_nop 0
	global_load_lds_dwordx4 v[214:215], off
	v_lshl_add_u64 v[214:215], v[220:221], 0, s[94:95]
	s_add_i32 m0, s20, 0x2000
	s_nop 0
	global_load_lds_dwordx4 v[214:215], off
	s_waitcnt vmcnt(6)
	s_waitcnt lgkmcnt(0)
	v_mfma_f32_16x16x32_bf16 v[62:65], v[66:69], v[150:153], v[62:65]
	v_mfma_f32_16x16x32_bf16 v[62:65], v[78:81], v[154:157], v[62:65]
	s_barrier
	s_setprio 1
	v_mfma_f32_16x16x32_bf16 v[58:61], v[98:101], v[154:157], v[58:61]
	v_mfma_f32_16x16x32_bf16 v[58:61], v[82:85], v[150:153], v[58:61]
	v_mfma_f32_16x16x32_bf16 v[42:45], v[82:85], v[158:161], v[42:45]
	v_mfma_f32_16x16x32_bf16 v[42:45], v[98:101], v[162:165], v[42:45]
	v_mfma_f32_16x16x32_bf16 v[46:49], v[78:81], v[162:165], v[46:49]
	v_mfma_f32_16x16x32_bf16 v[46:49], v[66:69], v[158:161], v[46:49]
	v_mfma_f32_16x16x32_bf16 v[30:33], v[66:69], v[170:173], v[30:33]
	v_mfma_f32_16x16x32_bf16 v[30:33], v[78:81], v[174:177], v[30:33]
	v_mfma_f32_16x16x32_bf16 v[26:29], v[98:101], v[174:177], v[26:29]
	v_mfma_f32_16x16x32_bf16 v[26:29], v[82:85], v[170:173], v[26:29]
	v_mfma_f32_16x16x32_bf16 v[10:13], v[82:85], v[178:181], v[10:13]
	v_mfma_f32_16x16x32_bf16 v[10:13], v[98:101], v[190:193], v[10:13]
	s_add_u32 s18, s18, 0x100
	v_mfma_f32_16x16x32_bf16 v[14:17], v[78:81], v[190:193], v[14:17]
	v_mfma_f32_16x16x32_bf16 v[14:17], v[66:69], v[178:181], v[14:17]
	s_addc_u32 s19, s19, 0
	v_mfma_f32_16x16x32_bf16 v[54:57], v[106:109], v[150:153], v[54:57]
	v_mfma_f32_16x16x32_bf16 v[54:57], v[118:121], v[154:157], v[54:57]
	s_add_u32 s51, s51, 0x100
	v_mfma_f32_16x16x32_bf16 v[50:53], v[142:145], v[154:157], v[50:53]
	v_mfma_f32_16x16x32_bf16 v[50:53], v[130:133], v[150:153], v[50:53]
	s_addc_u32 s54, s54, 0
	v_mfma_f32_16x16x32_bf16 v[34:37], v[130:133], v[158:161], v[34:37]
	v_mfma_f32_16x16x32_bf16 v[34:37], v[142:145], v[162:165], v[34:37]
	s_cmp_ge_u32 s55, s53
	v_mfma_f32_16x16x32_bf16 v[38:41], v[118:121], v[162:165], v[38:41]
	v_mfma_f32_16x16x32_bf16 v[38:41], v[106:109], v[158:161], v[38:41]
	s_mov_b32 s20, s55
	v_mfma_f32_16x16x32_bf16 v[22:25], v[106:109], v[170:173], v[22:25]
	v_mfma_f32_16x16x32_bf16 v[22:25], v[118:121], v[174:177], v[22:25]
	v_mfma_f32_16x16x32_bf16 v[18:21], v[142:145], v[174:177], v[18:21]
	v_mfma_f32_16x16x32_bf16 v[18:21], v[130:133], v[170:173], v[18:21]
	v_mfma_f32_16x16x32_bf16 v[2:5], v[130:133], v[178:181], v[2:5]
	v_mfma_f32_16x16x32_bf16 v[2:5], v[142:145], v[190:193], v[2:5]
	v_mfma_f32_16x16x32_bf16 v[6:9], v[118:121], v[190:193], v[6:9]
	v_mfma_f32_16x16x32_bf16 v[6:9], v[106:109], v[178:181], v[6:9]
	s_setprio 0
	s_barrier
	s_cbranch_scc0 .LBB0_850
	s_and_b64 vcc, exec, s[14:15]
	s_cbranch_vccz .LBB0_853
	s_barrier

.LBB0_875:
	s_sub_u32 vcc_lo, s20, s12
	s_subb_u32 vcc_hi, s21, 0
	v_lshl_add_u64 v[198:199], vcc, 0, v[210:211]
	s_mov_b32 m0, s51
	s_nop 0
	global_load_lds_dwordx4 v[198:199], off
	v_lshl_add_u64 v[198:199], vcc, 0, v[212:213]
	s_mov_b32 m0, s53
	s_nop 0
	global_load_lds_dwordx4 v[198:199], off
	ds_read_b128 v[130:133], v235
	ds_read_b128 v[134:137], v235 offset:1024
	ds_read_b128 v[138:141], v235 offset:2048
	ds_read_b128 v[142:145], v235 offset:3072
	ds_read_b128 v[146:149], v235 offset:16384
	ds_read_b128 v[150:153], v235 offset:17408
	ds_read_b128 v[154:157], v235 offset:18432
	ds_read_b128 v[158:161], v235 offset:19456
	ds_read_b128 v[162:165], v237
	ds_read_b128 v[166:169], v237 offset:1024
	ds_read_b128 v[170:173], v237 offset:2048
	ds_read_b128 v[174:177], v237 offset:3072
	ds_read_b128 v[178:181], v237 offset:4096
	ds_read_b128 v[182:185], v237 offset:5120
	ds_read_b128 v[186:189], v237 offset:6144
	ds_read_b128 v[190:193], v237 offset:7168
	s_add_i32 s29, s26, 2
	s_add_u32 s62, s20, 0x80
	s_addc_u32 s27, s21, 0
	s_add_i32 s64, 0, 0x10000
	s_cmp_eq_u32 s17, s26
	s_cselect_b32 s27, s7, s27
	s_cselect_b32 s26, s6, s62
	s_cselect_b32 s63, s19, s28
	s_cselect_b32 s62, s18, s23
	s_add_i32 s65, 0, 0x14000
	v_lshl_add_u64 v[198:199], s[20:21], 0, v[210:211]
	s_add_i32 m0, s37, 0xc000
	s_nop 0
	global_load_lds_dwordx4 v[198:199], off
	v_lshl_add_u64 v[198:199], s[20:21], 0, v[212:213]
	s_add_i32 m0, s37, 0xe000
	s_nop 0
	global_load_lds_dwordx4 v[198:199], off
	s_waitcnt vmcnt(8)
	s_waitcnt lgkmcnt(0)
	v_mfma_f32_16x16x32_bf16 v[126:129], v[130:133], v[162:165], v[126:129]
	v_mfma_f32_16x16x32_bf16 v[126:129], v[134:137], v[166:169], v[126:129]
	s_barrier
	s_setprio 1
	v_mfma_f32_16x16x32_bf16 v[122:125], v[142:145], v[166:169], v[122:125]
	v_mfma_f32_16x16x32_bf16 v[122:125], v[138:141], v[162:165], v[122:125]
	v_mfma_f32_16x16x32_bf16 v[106:109], v[138:141], v[170:173], v[106:109]
	v_mfma_f32_16x16x32_bf16 v[106:109], v[142:145], v[174:177], v[106:109]
	v_mfma_f32_16x16x32_bf16 v[110:113], v[134:137], v[174:177], v[110:113]
	v_mfma_f32_16x16x32_bf16 v[110:113], v[130:133], v[170:173], v[110:113]
	v_mfma_f32_16x16x32_bf16 v[94:97], v[130:133], v[178:181], v[94:97]
	v_mfma_f32_16x16x32_bf16 v[94:97], v[134:137], v[182:185], v[94:97]
	v_mfma_f32_16x16x32_bf16 v[90:93], v[142:145], v[182:185], v[90:93]
	v_mfma_f32_16x16x32_bf16 v[90:93], v[138:141], v[178:181], v[90:93]
	v_mfma_f32_16x16x32_bf16 v[74:77], v[138:141], v[186:189], v[74:77]
	v_mfma_f32_16x16x32_bf16 v[74:77], v[142:145], v[190:193], v[74:77]
	v_mfma_f32_16x16x32_bf16 v[78:81], v[134:137], v[190:193], v[78:81]
	v_mfma_f32_16x16x32_bf16 v[78:81], v[130:133], v[186:189], v[78:81]
	v_mfma_f32_16x16x32_bf16 v[118:121], v[146:149], v[162:165], v[118:121]
	v_mfma_f32_16x16x32_bf16 v[118:121], v[150:153], v[166:169], v[118:121]
	v_mfma_f32_16x16x32_bf16 v[114:117], v[158:161], v[166:169], v[114:117]
	v_mfma_f32_16x16x32_bf16 v[114:117], v[154:157], v[162:165], v[114:117]
	v_mfma_f32_16x16x32_bf16 v[98:101], v[154:157], v[170:173], v[98:101]
	v_mfma_f32_16x16x32_bf16 v[98:101], v[158:161], v[174:177], v[98:101]
	v_mfma_f32_16x16x32_bf16 v[102:105], v[150:153], v[174:177], v[102:105]
	v_mfma_f32_16x16x32_bf16 v[102:105], v[146:149], v[170:173], v[102:105]
	v_mfma_f32_16x16x32_bf16 v[86:89], v[146:149], v[178:181], v[86:89]
	v_mfma_f32_16x16x32_bf16 v[86:89], v[150:153], v[182:185], v[86:89]
	v_mfma_f32_16x16x32_bf16 v[82:85], v[158:161], v[182:185], v[82:85]
	v_mfma_f32_16x16x32_bf16 v[82:85], v[154:157], v[178:181], v[82:85]
	v_mfma_f32_16x16x32_bf16 v[66:69], v[154:157], v[186:189], v[66:69]
	v_mfma_f32_16x16x32_bf16 v[66:69], v[158:161], v[190:193], v[66:69]
	v_mfma_f32_16x16x32_bf16 v[70:73], v[150:153], v[190:193], v[70:73]
	v_mfma_f32_16x16x32_bf16 v[70:73], v[146:149], v[186:189], v[70:73]
	s_setprio 0
	s_barrier
	ds_read_b128 v[162:165], v237 offset:16384
	ds_read_b128 v[166:169], v237 offset:17408
	ds_read_b128 v[170:173], v237 offset:18432
	ds_read_b128 v[174:177], v237 offset:19456
	ds_read_b128 v[178:181], v237 offset:20480
	ds_read_b128 v[182:185], v237 offset:21504
	ds_read_b128 v[186:189], v237 offset:22528
	ds_read_b128 v[190:193], v237 offset:23552
	s_add_i32 s64, s64, s36
	v_lshl_add_u64 v[198:199], s[62:63], 0, v[194:195]
	s_mov_b32 m0, s64
	s_nop 0
	global_load_lds_dwordx4 v[198:199], off
	s_add_i32 m0, s64, 0x2000
	v_lshl_add_u64 v[214:215], s[62:63], 0, v[208:209]
	s_add_u32 s62, s62, s12
	s_addc_u32 s63, s63, 0
	s_add_i32 s64, s65, s36
	global_load_lds_dwordx4 v[214:215], off
	v_lshl_add_u64 v[216:217], s[62:63], 0, v[194:195]
	s_mov_b32 m0, s64
	v_lshl_add_u64 v[218:219], s[62:63], 0, v[208:209]
	global_load_lds_dwordx4 v[216:217], off
	s_add_i32 m0, s64, 0x2000
	v_lshl_add_u64 v[220:221], s[26:27], 0, v[204:205]
	global_load_lds_dwordx4 v[218:219], off
	v_lshl_add_u64 v[222:223], s[26:27], 0, v[206:207]
	s_waitcnt vmcnt(6)
	s_waitcnt lgkmcnt(0)
	v_mfma_f32_16x16x32_bf16 v[62:65], v[130:133], v[162:165], v[62:65]
	v_mfma_f32_16x16x32_bf16 v[62:65], v[134:137], v[166:169], v[62:65]
	s_barrier
	s_setprio 1
	v_mfma_f32_16x16x32_bf16 v[58:61], v[142:145], v[166:169], v[58:61]
	v_mfma_f32_16x16x32_bf16 v[58:61], v[138:141], v[162:165], v[58:61]
	v_mfma_f32_16x16x32_bf16 v[42:45], v[138:141], v[170:173], v[42:45]
	v_mfma_f32_16x16x32_bf16 v[42:45], v[142:145], v[174:177], v[42:45]
	v_mfma_f32_16x16x32_bf16 v[46:49], v[134:137], v[174:177], v[46:49]
	v_mfma_f32_16x16x32_bf16 v[46:49], v[130:133], v[170:173], v[46:49]
	v_mfma_f32_16x16x32_bf16 v[30:33], v[130:133], v[178:181], v[30:33]
	v_mfma_f32_16x16x32_bf16 v[30:33], v[134:137], v[182:185], v[30:33]
	v_mfma_f32_16x16x32_bf16 v[26:29], v[142:145], v[182:185], v[26:29]
	v_mfma_f32_16x16x32_bf16 v[26:29], v[138:141], v[178:181], v[26:29]
	v_mfma_f32_16x16x32_bf16 v[10:13], v[138:141], v[186:189], v[10:13]
	v_mfma_f32_16x16x32_bf16 v[10:13], v[142:145], v[190:193], v[10:13]
	v_mfma_f32_16x16x32_bf16 v[14:17], v[134:137], v[190:193], v[14:17]
	v_mfma_f32_16x16x32_bf16 v[14:17], v[130:133], v[186:189], v[14:17]
	v_mfma_f32_16x16x32_bf16 v[54:57], v[146:149], v[162:165], v[54:57]
	v_mfma_f32_16x16x32_bf16 v[54:57], v[150:153], v[166:169], v[54:57]
	v_mfma_f32_16x16x32_bf16 v[50:53], v[158:161], v[166:169], v[50:53]
	v_mfma_f32_16x16x32_bf16 v[50:53], v[154:157], v[162:165], v[50:53]
	v_mfma_f32_16x16x32_bf16 v[34:37], v[154:157], v[170:173], v[34:37]
	v_mfma_f32_16x16x32_bf16 v[34:37], v[158:161], v[174:177], v[34:37]
	v_mfma_f32_16x16x32_bf16 v[38:41], v[150:153], v[174:177], v[38:41]
	v_mfma_f32_16x16x32_bf16 v[38:41], v[146:149], v[170:173], v[38:41]
	v_mfma_f32_16x16x32_bf16 v[22:25], v[146:149], v[178:181], v[22:25]
	v_mfma_f32_16x16x32_bf16 v[22:25], v[150:153], v[182:185], v[22:25]
	v_mfma_f32_16x16x32_bf16 v[18:21], v[158:161], v[182:185], v[18:21]
	v_mfma_f32_16x16x32_bf16 v[18:21], v[154:157], v[178:181], v[18:21]
	v_mfma_f32_16x16x32_bf16 v[2:5], v[154:157], v[186:189], v[2:5]
	v_mfma_f32_16x16x32_bf16 v[2:5], v[158:161], v[190:193], v[2:5]
	v_mfma_f32_16x16x32_bf16 v[6:9], v[150:153], v[190:193], v[6:9]
	v_mfma_f32_16x16x32_bf16 v[6:9], v[146:149], v[186:189], v[6:9]
	s_setprio 0
	s_barrier
	s_mov_b32 m0, s37
	s_nop 0
	global_load_lds_dwordx4 v[220:221], off
	s_mov_b32 m0, s38
	s_nop 0
	global_load_lds_dwordx4 v[222:223], off
	ds_read_b128 v[130:133], v235 offset:32768
	ds_read_b128 v[134:137], v235 offset:33792
	ds_read_b128 v[138:141], v235 offset:34816
	ds_read_b128 v[142:145], v235 offset:35840
	ds_read_b128 v[146:149], v235 offset:49152
	ds_read_b128 v[150:153], v235 offset:50176
	ds_read_b128 v[154:157], v235 offset:51200
	ds_read_b128 v[158:161], v235 offset:52224
	ds_read_b128 v[162:165], v237 offset:32768
	ds_read_b128 v[166:169], v237 offset:33792
	ds_read_b128 v[170:173], v237 offset:34816
	ds_read_b128 v[174:177], v237 offset:35840
	ds_read_b128 v[178:181], v237 offset:36864
	ds_read_b128 v[182:185], v237 offset:37888
	ds_read_b128 v[186:189], v237 offset:38912
	ds_read_b128 v[190:193], v237 offset:39936
	s_add_i32 s62, 0, 0x18000
	s_add_i32 s63, 0, 0x1c000
	s_add_u32 s26, s26, s12
	s_addc_u32 s27, s27, 0
	s_mov_b32 m0, s39
	v_lshl_add_u64 v[224:225], s[26:27], 0, v[204:205]
	global_load_lds_dwordx4 v[224:225], off
	v_lshl_add_u64 v[224:225], s[26:27], 0, v[206:207]
	s_mov_b32 m0, s50
	s_nop 0
	global_load_lds_dwordx4 v[224:225], off
	s_waitcnt vmcnt(8)
	s_waitcnt lgkmcnt(0)
	v_mfma_f32_16x16x32_bf16 v[126:129], v[130:133], v[162:165], v[126:129]
	v_mfma_f32_16x16x32_bf16 v[126:129], v[134:137], v[166:169], v[126:129]
	s_barrier
	s_setprio 1
	v_mfma_f32_16x16x32_bf16 v[122:125], v[142:145], v[166:169], v[122:125]
	v_mfma_f32_16x16x32_bf16 v[122:125], v[138:141], v[162:165], v[122:125]
	v_mfma_f32_16x16x32_bf16 v[106:109], v[138:141], v[170:173], v[106:109]
	v_mfma_f32_16x16x32_bf16 v[106:109], v[142:145], v[174:177], v[106:109]
	v_mfma_f32_16x16x32_bf16 v[110:113], v[134:137], v[174:177], v[110:113]
	v_mfma_f32_16x16x32_bf16 v[110:113], v[130:133], v[170:173], v[110:113]
	v_mfma_f32_16x16x32_bf16 v[94:97], v[130:133], v[178:181], v[94:97]
	v_mfma_f32_16x16x32_bf16 v[94:97], v[134:137], v[182:185], v[94:97]
	v_mfma_f32_16x16x32_bf16 v[90:93], v[142:145], v[182:185], v[90:93]
	v_mfma_f32_16x16x32_bf16 v[90:93], v[138:141], v[178:181], v[90:93]
	v_mfma_f32_16x16x32_bf16 v[74:77], v[138:141], v[186:189], v[74:77]
	v_mfma_f32_16x16x32_bf16 v[74:77], v[142:145], v[190:193], v[74:77]
	v_mfma_f32_16x16x32_bf16 v[78:81], v[134:137], v[190:193], v[78:81]
	v_mfma_f32_16x16x32_bf16 v[78:81], v[130:133], v[186:189], v[78:81]
	v_mfma_f32_16x16x32_bf16 v[118:121], v[146:149], v[162:165], v[118:121]
	v_mfma_f32_16x16x32_bf16 v[118:121], v[150:153], v[166:169], v[118:121]
	v_mfma_f32_16x16x32_bf16 v[114:117], v[158:161], v[166:169], v[114:117]
	v_mfma_f32_16x16x32_bf16 v[114:117], v[154:157], v[162:165], v[114:117]
	v_mfma_f32_16x16x32_bf16 v[98:101], v[154:157], v[170:173], v[98:101]
	v_mfma_f32_16x16x32_bf16 v[98:101], v[158:161], v[174:177], v[98:101]
	v_mfma_f32_16x16x32_bf16 v[102:105], v[150:153], v[174:177], v[102:105]
	v_mfma_f32_16x16x32_bf16 v[102:105], v[146:149], v[170:173], v[102:105]
	v_mfma_f32_16x16x32_bf16 v[86:89], v[146:149], v[178:181], v[86:89]
	v_mfma_f32_16x16x32_bf16 v[86:89], v[150:153], v[182:185], v[86:89]
	v_mfma_f32_16x16x32_bf16 v[82:85], v[158:161], v[182:185], v[82:85]
	v_mfma_f32_16x16x32_bf16 v[82:85], v[154:157], v[178:181], v[82:85]
	v_mfma_f32_16x16x32_bf16 v[66:69], v[154:157], v[186:189], v[66:69]
	v_mfma_f32_16x16x32_bf16 v[66:69], v[158:161], v[190:193], v[66:69]
	v_mfma_f32_16x16x32_bf16 v[70:73], v[150:153], v[190:193], v[70:73]
	v_mfma_f32_16x16x32_bf16 v[70:73], v[146:149], v[186:189], v[70:73]
	s_setprio 0
	s_barrier
	ds_read_b128 v[162:165], v237 offset:49152
	ds_read_b128 v[166:169], v237 offset:50176
	ds_read_b128 v[170:173], v237 offset:51200
	ds_read_b128 v[174:177], v237 offset:52224
	ds_read_b128 v[178:181], v237 offset:53248
	ds_read_b128 v[182:185], v237 offset:54272
	ds_read_b128 v[186:189], v237 offset:55296
	ds_read_b128 v[190:193], v237 offset:56320
	s_add_i32 s26, s62, s36
	v_lshl_add_u64 v[198:199], v[198:199], 0, s[94:95]
	s_mov_b32 m0, s26
	s_nop 0
	global_load_lds_dwordx4 v[198:199], off
	v_lshl_add_u64 v[198:199], v[214:215], 0, s[94:95]
	s_add_i32 m0, s26, 0x2000
	s_add_i32 s26, s63, s36
	global_load_lds_dwordx4 v[198:199], off
	v_lshl_add_u64 v[198:199], v[216:217], 0, s[94:95]
	s_mov_b32 m0, s26
	s_nop 0
	global_load_lds_dwordx4 v[198:199], off
	v_lshl_add_u64 v[198:199], v[218:219], 0, s[94:95]
	s_add_i32 m0, s26, 0x2000
	s_nop 0
	global_load_lds_dwordx4 v[198:199], off
	s_waitcnt vmcnt(6)
	s_waitcnt lgkmcnt(0)
	v_mfma_f32_16x16x32_bf16 v[62:65], v[130:133], v[162:165], v[62:65]
	v_mfma_f32_16x16x32_bf16 v[62:65], v[134:137], v[166:169], v[62:65]
	s_barrier
	s_setprio 1
	v_mfma_f32_16x16x32_bf16 v[58:61], v[142:145], v[166:169], v[58:61]
	v_mfma_f32_16x16x32_bf16 v[58:61], v[138:141], v[162:165], v[58:61]
	v_mfma_f32_16x16x32_bf16 v[42:45], v[138:141], v[170:173], v[42:45]
	v_mfma_f32_16x16x32_bf16 v[42:45], v[142:145], v[174:177], v[42:45]
	v_mfma_f32_16x16x32_bf16 v[46:49], v[134:137], v[174:177], v[46:49]
	v_mfma_f32_16x16x32_bf16 v[46:49], v[130:133], v[170:173], v[46:49]
	v_mfma_f32_16x16x32_bf16 v[30:33], v[130:133], v[178:181], v[30:33]
	v_mfma_f32_16x16x32_bf16 v[30:33], v[134:137], v[182:185], v[30:33]
	v_mfma_f32_16x16x32_bf16 v[26:29], v[142:145], v[182:185], v[26:29]
	v_mfma_f32_16x16x32_bf16 v[26:29], v[138:141], v[178:181], v[26:29]
	v_mfma_f32_16x16x32_bf16 v[10:13], v[138:141], v[186:189], v[10:13]
	v_mfma_f32_16x16x32_bf16 v[10:13], v[142:145], v[190:193], v[10:13]
	s_add_u32 s20, s20, 0x100
	v_mfma_f32_16x16x32_bf16 v[14:17], v[134:137], v[190:193], v[14:17]
	v_mfma_f32_16x16x32_bf16 v[14:17], v[130:133], v[186:189], v[14:17]
	s_addc_u32 s21, s21, 0
	v_mfma_f32_16x16x32_bf16 v[54:57], v[146:149], v[162:165], v[54:57]
	v_mfma_f32_16x16x32_bf16 v[54:57], v[150:153], v[166:169], v[54:57]
	s_add_u32 s23, s23, 0x100
	v_mfma_f32_16x16x32_bf16 v[50:53], v[158:161], v[166:169], v[50:53]
	v_mfma_f32_16x16x32_bf16 v[50:53], v[154:157], v[162:165], v[50:53]
	s_addc_u32 s28, s28, 0
	v_mfma_f32_16x16x32_bf16 v[34:37], v[154:157], v[170:173], v[34:37]
	v_mfma_f32_16x16x32_bf16 v[34:37], v[158:161], v[174:177], v[34:37]
	s_cmp_ge_i32 s29, s25
	v_mfma_f32_16x16x32_bf16 v[38:41], v[150:153], v[174:177], v[38:41]
	v_mfma_f32_16x16x32_bf16 v[38:41], v[146:149], v[170:173], v[38:41]
	s_mov_b32 s26, s29
	v_mfma_f32_16x16x32_bf16 v[22:25], v[146:149], v[178:181], v[22:25]
	v_mfma_f32_16x16x32_bf16 v[22:25], v[150:153], v[182:185], v[22:25]
	v_mfma_f32_16x16x32_bf16 v[18:21], v[158:161], v[182:185], v[18:21]
	v_mfma_f32_16x16x32_bf16 v[18:21], v[154:157], v[178:181], v[18:21]
	v_mfma_f32_16x16x32_bf16 v[2:5], v[154:157], v[186:189], v[2:5]
	v_mfma_f32_16x16x32_bf16 v[2:5], v[158:161], v[190:193], v[2:5]
	v_mfma_f32_16x16x32_bf16 v[6:9], v[150:153], v[190:193], v[6:9]
	v_mfma_f32_16x16x32_bf16 v[6:9], v[146:149], v[186:189], v[6:9]
	s_setprio 0
	s_barrier
	s_cbranch_scc0 .LBB0_875
	v_readlane_b32 s64, v254, 51
	v_readlane_b32 s65, v254, 52
	s_branch .LBB0_878

.LBB0_973:
	s_add_u32 vcc_lo, s0, 0xffffc000
	s_addc_u32 vcc_hi, s1, -1
	v_lshl_add_u64 v[198:199], vcc, 0, v[146:147]
	s_mov_b32 m0, s59
	s_nop 0
	global_load_lds_dwordx4 v[198:199], off
	v_lshl_add_u64 v[198:199], vcc, 0, v[148:149]
	s_mov_b32 m0, s60
	s_nop 0
	global_load_lds_dwordx4 v[198:199], off
	ds_read_b128 v[130:133], v246
	ds_read_b128 v[134:137], v246 offset:1024
	ds_read_b128 v[150:153], v246 offset:2048
	ds_read_b128 v[154:157], v246 offset:3072
	ds_read_b128 v[158:161], v246 offset:16384
	ds_read_b128 v[162:165], v246 offset:17408
	ds_read_b128 v[166:169], v246 offset:18432
	ds_read_b128 v[170:173], v246 offset:19456
	ds_read_b128 v[174:177], v247
	ds_read_b128 v[178:181], v247 offset:1024
	ds_read_b128 v[182:185], v247 offset:2048
	ds_read_b128 v[186:189], v247 offset:3072
	ds_read_b128 v[190:193], v247 offset:4096
	ds_read_b128 v[204:207], v247 offset:5120
	ds_read_b128 v[208:211], v247 offset:6144
	ds_read_b128 v[212:215], v247 offset:7168
	s_add_u32 s4, s0, 0x100
	s_addc_u32 s5, s1, 0
	s_add_i32 s40, 0, 0x10000
	s_cmp_eq_u32 s39, 28
	s_cselect_b32 s11, s35, s5
	s_cselect_b32 s10, s34, s4
	s_cselect_b32 s7, s13, s38
	s_cselect_b32 s6, s29, s33
	s_add_i32 s41, 0, 0x14000
	v_lshl_add_u64 v[198:199], s[0:1], 0, v[146:147]
	s_add_i32 m0, s49, 0xc000
	s_nop 0
	global_load_lds_dwordx4 v[198:199], off
	v_lshl_add_u64 v[198:199], s[0:1], 0, v[148:149]
	s_add_i32 m0, s49, 0xe000
	s_nop 0
	global_load_lds_dwordx4 v[198:199], off
	s_waitcnt vmcnt(8)
	s_waitcnt lgkmcnt(0)
	v_mfma_f32_16x16x32_bf16 v[126:129], v[130:133], v[174:177], v[126:129]
	v_mfma_f32_16x16x32_bf16 v[126:129], v[134:137], v[178:181], v[126:129]
	s_barrier
	s_setprio 1
	v_mfma_f32_16x16x32_bf16 v[62:65], v[154:157], v[178:181], v[62:65]
	v_mfma_f32_16x16x32_bf16 v[62:65], v[150:153], v[174:177], v[62:65]
	v_mfma_f32_16x16x32_bf16 v[58:61], v[150:153], v[182:185], v[58:61]
	v_mfma_f32_16x16x32_bf16 v[58:61], v[154:157], v[186:189], v[58:61]
	v_mfma_f32_16x16x32_bf16 v[122:125], v[134:137], v[186:189], v[122:125]
	v_mfma_f32_16x16x32_bf16 v[122:125], v[130:133], v[182:185], v[122:125]
	v_mfma_f32_16x16x32_bf16 v[114:117], v[130:133], v[190:193], v[114:117]
	v_mfma_f32_16x16x32_bf16 v[114:117], v[134:137], v[204:207], v[114:117]
	v_mfma_f32_16x16x32_bf16 v[50:53], v[154:157], v[204:207], v[50:53]
	v_mfma_f32_16x16x32_bf16 v[50:53], v[150:153], v[190:193], v[50:53]
	v_mfma_f32_16x16x32_bf16 v[42:45], v[150:153], v[208:211], v[42:45]
	v_mfma_f32_16x16x32_bf16 v[42:45], v[154:157], v[212:215], v[42:45]
	v_mfma_f32_16x16x32_bf16 v[106:109], v[134:137], v[212:215], v[106:109]
	v_mfma_f32_16x16x32_bf16 v[106:109], v[130:133], v[208:211], v[106:109]
	v_mfma_f32_16x16x32_bf16 v[118:121], v[158:161], v[174:177], v[118:121]
	v_mfma_f32_16x16x32_bf16 v[118:121], v[162:165], v[178:181], v[118:121]
	v_mfma_f32_16x16x32_bf16 v[54:57], v[170:173], v[178:181], v[54:57]
	v_mfma_f32_16x16x32_bf16 v[54:57], v[166:169], v[174:177], v[54:57]
	v_mfma_f32_16x16x32_bf16 v[46:49], v[166:169], v[182:185], v[46:49]
	v_mfma_f32_16x16x32_bf16 v[46:49], v[170:173], v[186:189], v[46:49]
	v_mfma_f32_16x16x32_bf16 v[110:113], v[162:165], v[186:189], v[110:113]
	v_mfma_f32_16x16x32_bf16 v[110:113], v[158:161], v[182:185], v[110:113]
	v_mfma_f32_16x16x32_bf16 v[102:105], v[158:161], v[190:193], v[102:105]
	v_mfma_f32_16x16x32_bf16 v[102:105], v[162:165], v[204:207], v[102:105]
	v_mfma_f32_16x16x32_bf16 v[38:41], v[170:173], v[204:207], v[38:41]
	v_mfma_f32_16x16x32_bf16 v[38:41], v[166:169], v[190:193], v[38:41]
	v_mfma_f32_16x16x32_bf16 v[34:37], v[166:169], v[208:211], v[34:37]
	v_mfma_f32_16x16x32_bf16 v[34:37], v[170:173], v[212:215], v[34:37]
	v_mfma_f32_16x16x32_bf16 v[98:101], v[162:165], v[212:215], v[98:101]
	v_mfma_f32_16x16x32_bf16 v[98:101], v[158:161], v[208:211], v[98:101]
	s_setprio 0
	s_barrier
	ds_read_b128 v[174:177], v247 offset:16384
	ds_read_b128 v[178:181], v247 offset:17408
	ds_read_b128 v[182:185], v247 offset:18432
	ds_read_b128 v[186:189], v247 offset:19456
	ds_read_b128 v[190:193], v247 offset:20480
	ds_read_b128 v[204:207], v247 offset:21504
	ds_read_b128 v[208:211], v247 offset:22528
	ds_read_b128 v[212:215], v247 offset:23552
	s_add_i32 s0, s40, s48
	v_lshl_add_u64 v[198:199], s[6:7], 0, v[140:141]
	s_mov_b32 m0, s0
	s_nop 0
	global_load_lds_dwordx4 v[198:199], off
	s_add_i32 m0, s0, 0x2000
	s_add_u32 s0, s6, 0x80000
	v_lshl_add_u64 v[200:201], s[6:7], 0, v[144:145]
	s_addc_u32 s1, s7, 0
	s_add_i32 s40, s41, s48
	global_load_lds_dwordx4 v[200:201], off
	v_lshl_add_u64 v[216:217], s[0:1], 0, v[140:141]
	s_mov_b32 m0, s40
	v_lshl_add_u64 v[218:219], s[10:11], 0, v[142:143]
	global_load_lds_dwordx4 v[216:217], off
	v_lshl_add_u64 v[216:217], s[0:1], 0, v[144:145]
	s_add_i32 m0, s40, 0x2000
	s_nop 0
	global_load_lds_dwordx4 v[216:217], off
	v_lshl_add_u64 v[216:217], s[10:11], 0, v[138:139]
	s_waitcnt vmcnt(6)
	s_waitcnt lgkmcnt(0)
	v_mfma_f32_16x16x32_bf16 v[94:97], v[130:133], v[174:177], v[94:97]
	v_mfma_f32_16x16x32_bf16 v[94:97], v[134:137], v[178:181], v[94:97]
	s_barrier
	s_setprio 1
	v_mfma_f32_16x16x32_bf16 v[30:33], v[154:157], v[178:181], v[30:33]
	v_mfma_f32_16x16x32_bf16 v[30:33], v[150:153], v[174:177], v[30:33]
	v_mfma_f32_16x16x32_bf16 v[26:29], v[150:153], v[182:185], v[26:29]
	v_mfma_f32_16x16x32_bf16 v[26:29], v[154:157], v[186:189], v[26:29]
	v_mfma_f32_16x16x32_bf16 v[90:93], v[134:137], v[186:189], v[90:93]
	v_mfma_f32_16x16x32_bf16 v[90:93], v[130:133], v[182:185], v[90:93]
	v_mfma_f32_16x16x32_bf16 v[82:85], v[130:133], v[190:193], v[82:85]
	v_mfma_f32_16x16x32_bf16 v[82:85], v[134:137], v[204:207], v[82:85]
	v_mfma_f32_16x16x32_bf16 v[18:21], v[154:157], v[204:207], v[18:21]
	v_mfma_f32_16x16x32_bf16 v[18:21], v[150:153], v[190:193], v[18:21]
	v_mfma_f32_16x16x32_bf16 v[10:13], v[150:153], v[208:211], v[10:13]
	v_mfma_f32_16x16x32_bf16 v[10:13], v[154:157], v[212:215], v[10:13]
	v_mfma_f32_16x16x32_bf16 v[74:77], v[134:137], v[212:215], v[74:77]
	v_mfma_f32_16x16x32_bf16 v[74:77], v[130:133], v[208:211], v[74:77]
	v_mfma_f32_16x16x32_bf16 v[86:89], v[158:161], v[174:177], v[86:89]
	v_mfma_f32_16x16x32_bf16 v[86:89], v[162:165], v[178:181], v[86:89]
	v_mfma_f32_16x16x32_bf16 v[22:25], v[170:173], v[178:181], v[22:25]
	v_mfma_f32_16x16x32_bf16 v[22:25], v[166:169], v[174:177], v[22:25]
	v_mfma_f32_16x16x32_bf16 v[14:17], v[166:169], v[182:185], v[14:17]
	v_mfma_f32_16x16x32_bf16 v[14:17], v[170:173], v[186:189], v[14:17]
	v_mfma_f32_16x16x32_bf16 v[78:81], v[162:165], v[186:189], v[78:81]
	v_mfma_f32_16x16x32_bf16 v[78:81], v[158:161], v[182:185], v[78:81]
	v_mfma_f32_16x16x32_bf16 v[70:73], v[158:161], v[190:193], v[70:73]
	v_mfma_f32_16x16x32_bf16 v[70:73], v[162:165], v[204:207], v[70:73]
	v_mfma_f32_16x16x32_bf16 v[6:9], v[170:173], v[204:207], v[6:9]
	v_mfma_f32_16x16x32_bf16 v[6:9], v[166:169], v[190:193], v[6:9]
	v_mfma_f32_16x16x32_bf16 v[2:5], v[166:169], v[208:211], v[2:5]
	v_mfma_f32_16x16x32_bf16 v[2:5], v[170:173], v[212:215], v[2:5]
	v_mfma_f32_16x16x32_bf16 v[66:69], v[162:165], v[212:215], v[66:69]
	v_mfma_f32_16x16x32_bf16 v[66:69], v[158:161], v[208:211], v[66:69]
	s_setprio 0
	s_barrier
	s_mov_b32 m0, s49
	s_nop 0
	global_load_lds_dwordx4 v[216:217], off
	s_mov_b32 m0, s70
	s_nop 0
	global_load_lds_dwordx4 v[218:219], off
	ds_read_b128 v[130:133], v246 offset:32768
	ds_read_b128 v[134:137], v246 offset:33792
	ds_read_b128 v[150:153], v246 offset:34816
	ds_read_b128 v[154:157], v246 offset:35840
	ds_read_b128 v[158:161], v246 offset:49152
	ds_read_b128 v[162:165], v246 offset:50176
	ds_read_b128 v[166:169], v246 offset:51200
	ds_read_b128 v[170:173], v246 offset:52224
	ds_read_b128 v[174:177], v247 offset:32768
	ds_read_b128 v[178:181], v247 offset:33792
	ds_read_b128 v[182:185], v247 offset:34816
	ds_read_b128 v[186:189], v247 offset:35840
	ds_read_b128 v[190:193], v247 offset:36864
	ds_read_b128 v[204:207], v247 offset:37888
	ds_read_b128 v[208:211], v247 offset:38912
	ds_read_b128 v[212:215], v247 offset:39936
	s_add_i32 s40, 0, 0x18000
	s_add_i32 s41, 0, 0x1c000
	s_add_u32 s0, s10, 0x4000
	s_addc_u32 s1, s11, 0
	s_mov_b32 m0, s71
	v_lshl_add_u64 v[220:221], s[0:1], 0, v[138:139]
	global_load_lds_dwordx4 v[220:221], off
	v_lshl_add_u64 v[220:221], s[0:1], 0, v[142:143]
	s_mov_b32 m0, s73
	s_nop 0
	global_load_lds_dwordx4 v[220:221], off
	s_waitcnt vmcnt(8)
	s_waitcnt lgkmcnt(0)
	v_mfma_f32_16x16x32_bf16 v[126:129], v[130:133], v[174:177], v[126:129]
	v_mfma_f32_16x16x32_bf16 v[126:129], v[134:137], v[178:181], v[126:129]
	s_barrier
	s_setprio 1
	v_mfma_f32_16x16x32_bf16 v[62:65], v[154:157], v[178:181], v[62:65]
	v_mfma_f32_16x16x32_bf16 v[62:65], v[150:153], v[174:177], v[62:65]
	v_mfma_f32_16x16x32_bf16 v[58:61], v[150:153], v[182:185], v[58:61]
	v_mfma_f32_16x16x32_bf16 v[58:61], v[154:157], v[186:189], v[58:61]
	v_mfma_f32_16x16x32_bf16 v[122:125], v[134:137], v[186:189], v[122:125]
	v_mfma_f32_16x16x32_bf16 v[122:125], v[130:133], v[182:185], v[122:125]
	v_mfma_f32_16x16x32_bf16 v[114:117], v[130:133], v[190:193], v[114:117]
	v_mfma_f32_16x16x32_bf16 v[114:117], v[134:137], v[204:207], v[114:117]
	v_mfma_f32_16x16x32_bf16 v[50:53], v[154:157], v[204:207], v[50:53]
	v_mfma_f32_16x16x32_bf16 v[50:53], v[150:153], v[190:193], v[50:53]
	v_mfma_f32_16x16x32_bf16 v[42:45], v[150:153], v[208:211], v[42:45]
	v_mfma_f32_16x16x32_bf16 v[42:45], v[154:157], v[212:215], v[42:45]
	v_mfma_f32_16x16x32_bf16 v[106:109], v[134:137], v[212:215], v[106:109]
	v_mfma_f32_16x16x32_bf16 v[106:109], v[130:133], v[208:211], v[106:109]
	v_mfma_f32_16x16x32_bf16 v[118:121], v[158:161], v[174:177], v[118:121]
	v_mfma_f32_16x16x32_bf16 v[118:121], v[162:165], v[178:181], v[118:121]
	v_mfma_f32_16x16x32_bf16 v[54:57], v[170:173], v[178:181], v[54:57]
	v_mfma_f32_16x16x32_bf16 v[54:57], v[166:169], v[174:177], v[54:57]
	v_mfma_f32_16x16x32_bf16 v[46:49], v[166:169], v[182:185], v[46:49]
	v_mfma_f32_16x16x32_bf16 v[46:49], v[170:173], v[186:189], v[46:49]
	v_mfma_f32_16x16x32_bf16 v[110:113], v[162:165], v[186:189], v[110:113]
	v_mfma_f32_16x16x32_bf16 v[110:113], v[158:161], v[182:185], v[110:113]
	v_mfma_f32_16x16x32_bf16 v[102:105], v[158:161], v[190:193], v[102:105]
	v_mfma_f32_16x16x32_bf16 v[102:105], v[162:165], v[204:207], v[102:105]
	v_mfma_f32_16x16x32_bf16 v[38:41], v[170:173], v[204:207], v[38:41]
	v_mfma_f32_16x16x32_bf16 v[38:41], v[166:169], v[190:193], v[38:41]
	v_mfma_f32_16x16x32_bf16 v[34:37], v[166:169], v[208:211], v[34:37]
	v_mfma_f32_16x16x32_bf16 v[34:37], v[170:173], v[212:215], v[34:37]
	v_mfma_f32_16x16x32_bf16 v[98:101], v[162:165], v[212:215], v[98:101]
	v_mfma_f32_16x16x32_bf16 v[98:101], v[158:161], v[208:211], v[98:101]
	s_setprio 0
	s_barrier
	ds_read_b128 v[174:177], v247 offset:49152
	ds_read_b128 v[178:181], v247 offset:50176
	ds_read_b128 v[182:185], v247 offset:51200
	ds_read_b128 v[186:189], v247 offset:52224
	ds_read_b128 v[190:193], v247 offset:53248
	ds_read_b128 v[204:207], v247 offset:54272
	ds_read_b128 v[208:211], v247 offset:55296
	ds_read_b128 v[212:215], v247 offset:56320
	s_add_i32 s0, s40, s48
	v_lshl_add_u64 v[198:199], v[198:199], 0, s[94:95]
	s_mov_b32 m0, s0
	s_nop 0
	global_load_lds_dwordx4 v[198:199], off
	s_add_i32 m0, s0, 0x2000
	s_add_u32 s0, s6, 0x80080
	v_lshl_add_u64 v[198:199], v[200:201], 0, s[94:95]
	s_addc_u32 s1, s7, 0
	s_add_i32 s6, s41, s48
	global_load_lds_dwordx4 v[198:199], off
	v_lshl_add_u64 v[198:199], s[0:1], 0, v[140:141]
	s_mov_b32 m0, s6
	s_nop 0
	global_load_lds_dwordx4 v[198:199], off
	v_lshl_add_u64 v[198:199], s[0:1], 0, v[144:145]
	s_add_i32 m0, s6, 0x2000
	s_nop 0
	global_load_lds_dwordx4 v[198:199], off
	s_waitcnt vmcnt(6)
	s_waitcnt lgkmcnt(0)
	v_mfma_f32_16x16x32_bf16 v[94:97], v[130:133], v[174:177], v[94:97]
	v_mfma_f32_16x16x32_bf16 v[94:97], v[134:137], v[178:181], v[94:97]
	s_barrier
	s_setprio 1
	v_mfma_f32_16x16x32_bf16 v[30:33], v[154:157], v[178:181], v[30:33]
	v_mfma_f32_16x16x32_bf16 v[30:33], v[150:153], v[174:177], v[30:33]
	v_mfma_f32_16x16x32_bf16 v[26:29], v[150:153], v[182:185], v[26:29]
	v_mfma_f32_16x16x32_bf16 v[26:29], v[154:157], v[186:189], v[26:29]
	v_mfma_f32_16x16x32_bf16 v[90:93], v[134:137], v[186:189], v[90:93]
	v_mfma_f32_16x16x32_bf16 v[90:93], v[130:133], v[182:185], v[90:93]
	v_mfma_f32_16x16x32_bf16 v[82:85], v[130:133], v[190:193], v[82:85]
	v_mfma_f32_16x16x32_bf16 v[82:85], v[134:137], v[204:207], v[82:85]
	v_mfma_f32_16x16x32_bf16 v[18:21], v[154:157], v[204:207], v[18:21]
	v_mfma_f32_16x16x32_bf16 v[18:21], v[150:153], v[190:193], v[18:21]
	v_mfma_f32_16x16x32_bf16 v[10:13], v[150:153], v[208:211], v[10:13]
	v_mfma_f32_16x16x32_bf16 v[10:13], v[154:157], v[212:215], v[10:13]
	s_add_i32 s39, s39, 2
	v_mfma_f32_16x16x32_bf16 v[74:77], v[134:137], v[212:215], v[74:77]
	v_mfma_f32_16x16x32_bf16 v[74:77], v[130:133], v[208:211], v[74:77]
	s_add_u32 s33, s33, 0x100
	v_mfma_f32_16x16x32_bf16 v[86:89], v[158:161], v[174:177], v[86:89]
	v_mfma_f32_16x16x32_bf16 v[86:89], v[162:165], v[178:181], v[86:89]
	s_addc_u32 s38, s38, 0
	v_mfma_f32_16x16x32_bf16 v[22:25], v[170:173], v[178:181], v[22:25]
	v_mfma_f32_16x16x32_bf16 v[22:25], v[166:169], v[174:177], v[22:25]
	s_cmp_gt_u32 s39, 29
	v_mfma_f32_16x16x32_bf16 v[14:17], v[166:169], v[182:185], v[14:17]
	v_mfma_f32_16x16x32_bf16 v[14:17], v[170:173], v[186:189], v[14:17]
	s_mov_b64 s[0:1], s[4:5]
	v_mfma_f32_16x16x32_bf16 v[78:81], v[162:165], v[186:189], v[78:81]
	v_mfma_f32_16x16x32_bf16 v[78:81], v[158:161], v[182:185], v[78:81]
	v_mfma_f32_16x16x32_bf16 v[70:73], v[158:161], v[190:193], v[70:73]
	v_mfma_f32_16x16x32_bf16 v[70:73], v[162:165], v[204:207], v[70:73]
	v_mfma_f32_16x16x32_bf16 v[6:9], v[170:173], v[204:207], v[6:9]
	v_mfma_f32_16x16x32_bf16 v[6:9], v[166:169], v[190:193], v[6:9]
	v_mfma_f32_16x16x32_bf16 v[2:5], v[166:169], v[208:211], v[2:5]
	v_mfma_f32_16x16x32_bf16 v[2:5], v[170:173], v[212:215], v[2:5]
	v_mfma_f32_16x16x32_bf16 v[66:69], v[162:165], v[212:215], v[66:69]
	v_mfma_f32_16x16x32_bf16 v[66:69], v[158:161], v[208:211], v[66:69]
	s_setprio 0
	s_barrier
	s_cbranch_scc0 .LBB0_973
	s_and_b64 vcc, exec, s[26:27]
	s_cbranch_vccz .LBB0_976
	s_barrier

.LBB0_1441:
	s_add_u32 vcc_lo, s18, 0xffea0000
	s_addc_u32 vcc_hi, s19, -1
	v_lshl_add_u64 v[200:201], vcc, 0, v[210:211]
	s_mov_b32 m0, s38
	s_nop 0
	global_load_lds_dwordx4 v[200:201], off
	v_lshl_add_u64 v[200:201], vcc, 0, v[212:213]
	s_mov_b32 m0, s40
	s_nop 0
	global_load_lds_dwordx4 v[200:201], off
	ds_read_b128 v[66:69], v198
	ds_read_b128 v[78:81], v198 offset:1024
	ds_read_b128 v[86:89], v198 offset:2048
	ds_read_b128 v[98:101], v198 offset:3072
	ds_read_b128 v[106:109], v198 offset:16384
	ds_read_b128 v[118:121], v198 offset:17408
	ds_read_b128 v[130:133], v198 offset:18432
	ds_read_b128 v[142:145], v198 offset:19456
	ds_read_b128 v[150:153], v234
	ds_read_b128 v[154:157], v234 offset:1024
	ds_read_b128 v[158:161], v234 offset:2048
	ds_read_b128 v[162:165], v234 offset:3072
	ds_read_b128 v[170:173], v234 offset:4096
	ds_read_b128 v[174:177], v234 offset:5120
	ds_read_b128 v[178:181], v234 offset:6144
	ds_read_b128 v[190:193], v234 offset:7168
	s_add_u32 s20, s18, 0x100
	s_addc_u32 s21, s19, 0
	s_add_i32 s49, 0, 0x10000
	s_cmpk_eq_i32 s48, 0x54
	s_cselect_b32 s25, s1, s21
	s_cselect_b32 s24, s0, s20
	s_cselect_b32 s23, s17, s47
	s_cselect_b32 s22, s16, s46
	s_add_i32 s50, 0, 0x14000
	v_lshl_add_u64 v[200:201], s[18:19], 0, v[210:211]
	s_add_i32 m0, s28, 0xc000
	s_nop 0
	global_load_lds_dwordx4 v[200:201], off
	v_lshl_add_u64 v[200:201], s[18:19], 0, v[212:213]
	s_add_i32 m0, s28, 0xe000
	s_nop 0
	global_load_lds_dwordx4 v[200:201], off
	s_waitcnt vmcnt(8)
	s_waitcnt lgkmcnt(0)
	v_mfma_f32_16x16x32_bf16 v[186:189], v[66:69], v[150:153], v[186:189]
	v_mfma_f32_16x16x32_bf16 v[186:189], v[78:81], v[154:157], v[186:189]
	s_barrier
	s_setprio 1
	v_mfma_f32_16x16x32_bf16 v[182:185], v[98:101], v[154:157], v[182:185]
	v_mfma_f32_16x16x32_bf16 v[182:185], v[86:89], v[150:153], v[182:185]
	v_mfma_f32_16x16x32_bf16 v[134:137], v[86:89], v[158:161], v[134:137]
	v_mfma_f32_16x16x32_bf16 v[134:137], v[98:101], v[162:165], v[134:137]
	v_mfma_f32_16x16x32_bf16 v[138:141], v[78:81], v[162:165], v[138:141]
	v_mfma_f32_16x16x32_bf16 v[138:141], v[66:69], v[158:161], v[138:141]
	v_mfma_f32_16x16x32_bf16 v[114:117], v[66:69], v[170:173], v[114:117]
	v_mfma_f32_16x16x32_bf16 v[114:117], v[78:81], v[174:177], v[114:117]
	v_mfma_f32_16x16x32_bf16 v[110:113], v[98:101], v[174:177], v[110:113]
	v_mfma_f32_16x16x32_bf16 v[110:113], v[86:89], v[170:173], v[110:113]
	v_mfma_f32_16x16x32_bf16 v[82:85], v[86:89], v[178:181], v[82:85]
	v_mfma_f32_16x16x32_bf16 v[82:85], v[98:101], v[190:193], v[82:85]
	v_mfma_f32_16x16x32_bf16 v[90:93], v[78:81], v[190:193], v[90:93]
	v_mfma_f32_16x16x32_bf16 v[90:93], v[66:69], v[178:181], v[90:93]
	v_mfma_f32_16x16x32_bf16 v[166:169], v[106:109], v[150:153], v[166:169]
	v_mfma_f32_16x16x32_bf16 v[166:169], v[118:121], v[154:157], v[166:169]
	v_mfma_f32_16x16x32_bf16 v[146:149], v[142:145], v[154:157], v[146:149]
	v_mfma_f32_16x16x32_bf16 v[146:149], v[130:133], v[150:153], v[146:149]
	v_mfma_f32_16x16x32_bf16 v[122:125], v[130:133], v[158:161], v[122:125]
	v_mfma_f32_16x16x32_bf16 v[122:125], v[142:145], v[162:165], v[122:125]
	v_mfma_f32_16x16x32_bf16 v[126:129], v[118:121], v[162:165], v[126:129]
	v_mfma_f32_16x16x32_bf16 v[126:129], v[106:109], v[158:161], v[126:129]
	v_mfma_f32_16x16x32_bf16 v[102:105], v[106:109], v[170:173], v[102:105]
	v_mfma_f32_16x16x32_bf16 v[102:105], v[118:121], v[174:177], v[102:105]
	v_mfma_f32_16x16x32_bf16 v[94:97], v[142:145], v[174:177], v[94:97]
	v_mfma_f32_16x16x32_bf16 v[94:97], v[130:133], v[170:173], v[94:97]
	v_mfma_f32_16x16x32_bf16 v[70:73], v[130:133], v[178:181], v[70:73]
	v_mfma_f32_16x16x32_bf16 v[70:73], v[142:145], v[190:193], v[70:73]
	v_mfma_f32_16x16x32_bf16 v[74:77], v[118:121], v[190:193], v[74:77]
	v_mfma_f32_16x16x32_bf16 v[74:77], v[106:109], v[178:181], v[74:77]
	s_setprio 0
	s_barrier
	ds_read_b128 v[150:153], v234 offset:16384
	ds_read_b128 v[154:157], v234 offset:17408
	ds_read_b128 v[158:161], v234 offset:18432
	ds_read_b128 v[162:165], v234 offset:19456
	ds_read_b128 v[170:173], v234 offset:20480
	ds_read_b128 v[174:177], v234 offset:21504
	ds_read_b128 v[178:181], v234 offset:22528
	ds_read_b128 v[190:193], v234 offset:23552
	s_add_i32 s18, s49, s26
	v_lshl_add_u64 v[200:201], s[22:23], 0, v[194:195]
	s_mov_b32 m0, s18
	s_nop 0
	global_load_lds_dwordx4 v[200:201], off
	s_add_i32 m0, s18, 0x2000
	s_add_u32 s18, s22, 0x160000
	v_lshl_add_u64 v[214:215], s[22:23], 0, v[204:205]
	s_addc_u32 s19, s23, 0
	s_add_i32 s49, s50, s26
	global_load_lds_dwordx4 v[214:215], off
	v_lshl_add_u64 v[216:217], s[18:19], 0, v[194:195]
	s_mov_b32 m0, s49
	v_lshl_add_u64 v[218:219], s[24:25], 0, v[206:207]
	global_load_lds_dwordx4 v[216:217], off
	v_lshl_add_u64 v[216:217], s[18:19], 0, v[204:205]
	s_add_i32 m0, s49, 0x2000
	s_nop 0
	global_load_lds_dwordx4 v[216:217], off
	v_lshl_add_u64 v[216:217], s[24:25], 0, v[208:209]
	s_waitcnt vmcnt(6)
	s_waitcnt lgkmcnt(0)
	v_mfma_f32_16x16x32_bf16 v[62:65], v[66:69], v[150:153], v[62:65]
	v_mfma_f32_16x16x32_bf16 v[62:65], v[78:81], v[154:157], v[62:65]
	s_barrier
	s_setprio 1
	v_mfma_f32_16x16x32_bf16 v[58:61], v[98:101], v[154:157], v[58:61]
	v_mfma_f32_16x16x32_bf16 v[58:61], v[86:89], v[150:153], v[58:61]
	v_mfma_f32_16x16x32_bf16 v[42:45], v[86:89], v[158:161], v[42:45]
	v_mfma_f32_16x16x32_bf16 v[42:45], v[98:101], v[162:165], v[42:45]
	v_mfma_f32_16x16x32_bf16 v[46:49], v[78:81], v[162:165], v[46:49]
	v_mfma_f32_16x16x32_bf16 v[46:49], v[66:69], v[158:161], v[46:49]
	v_mfma_f32_16x16x32_bf16 v[30:33], v[66:69], v[170:173], v[30:33]
	v_mfma_f32_16x16x32_bf16 v[30:33], v[78:81], v[174:177], v[30:33]
	v_mfma_f32_16x16x32_bf16 v[26:29], v[98:101], v[174:177], v[26:29]
	v_mfma_f32_16x16x32_bf16 v[26:29], v[86:89], v[170:173], v[26:29]
	v_mfma_f32_16x16x32_bf16 v[10:13], v[86:89], v[178:181], v[10:13]
	v_mfma_f32_16x16x32_bf16 v[10:13], v[98:101], v[190:193], v[10:13]
	v_mfma_f32_16x16x32_bf16 v[14:17], v[78:81], v[190:193], v[14:17]
	v_mfma_f32_16x16x32_bf16 v[14:17], v[66:69], v[178:181], v[14:17]
	v_mfma_f32_16x16x32_bf16 v[54:57], v[106:109], v[150:153], v[54:57]
	v_mfma_f32_16x16x32_bf16 v[54:57], v[118:121], v[154:157], v[54:57]
	v_mfma_f32_16x16x32_bf16 v[50:53], v[142:145], v[154:157], v[50:53]
	v_mfma_f32_16x16x32_bf16 v[50:53], v[130:133], v[150:153], v[50:53]
	v_mfma_f32_16x16x32_bf16 v[34:37], v[130:133], v[158:161], v[34:37]
	v_mfma_f32_16x16x32_bf16 v[34:37], v[142:145], v[162:165], v[34:37]
	v_mfma_f32_16x16x32_bf16 v[38:41], v[118:121], v[162:165], v[38:41]
	v_mfma_f32_16x16x32_bf16 v[38:41], v[106:109], v[158:161], v[38:41]
	v_mfma_f32_16x16x32_bf16 v[22:25], v[106:109], v[170:173], v[22:25]
	v_mfma_f32_16x16x32_bf16 v[22:25], v[118:121], v[174:177], v[22:25]
	v_mfma_f32_16x16x32_bf16 v[18:21], v[142:145], v[174:177], v[18:21]
	v_mfma_f32_16x16x32_bf16 v[18:21], v[130:133], v[170:173], v[18:21]
	v_mfma_f32_16x16x32_bf16 v[2:5], v[130:133], v[178:181], v[2:5]
	v_mfma_f32_16x16x32_bf16 v[2:5], v[142:145], v[190:193], v[2:5]
	v_mfma_f32_16x16x32_bf16 v[6:9], v[118:121], v[190:193], v[6:9]
	v_mfma_f32_16x16x32_bf16 v[6:9], v[106:109], v[178:181], v[6:9]
	s_setprio 0
	s_barrier
	s_mov_b32 m0, s28
	s_nop 0
	global_load_lds_dwordx4 v[216:217], off
	s_mov_b32 m0, s29
	s_nop 0
	global_load_lds_dwordx4 v[218:219], off
	ds_read_b128 v[66:69], v198 offset:32768
	ds_read_b128 v[78:81], v198 offset:33792
	ds_read_b128 v[86:89], v198 offset:34816
	ds_read_b128 v[98:101], v198 offset:35840
	ds_read_b128 v[106:109], v198 offset:49152
	ds_read_b128 v[118:121], v198 offset:50176
	ds_read_b128 v[130:133], v198 offset:51200
	ds_read_b128 v[142:145], v198 offset:52224
	ds_read_b128 v[150:153], v234 offset:32768
	ds_read_b128 v[154:157], v234 offset:33792
	ds_read_b128 v[158:161], v234 offset:34816
	ds_read_b128 v[162:165], v234 offset:35840
	ds_read_b128 v[170:173], v234 offset:36864
	ds_read_b128 v[174:177], v234 offset:37888
	ds_read_b128 v[178:181], v234 offset:38912
	ds_read_b128 v[190:193], v234 offset:39936
	s_add_i32 s49, 0, 0x18000
	s_add_i32 s50, 0, 0x1c000
	s_add_u32 s18, s24, 0x160000
	s_addc_u32 s19, s25, 0
	s_mov_b32 m0, s33
	v_lshl_add_u64 v[220:221], s[18:19], 0, v[208:209]
	global_load_lds_dwordx4 v[220:221], off
	v_lshl_add_u64 v[220:221], s[18:19], 0, v[206:207]
	s_mov_b32 m0, s37
	s_nop 0
	global_load_lds_dwordx4 v[220:221], off
	s_waitcnt vmcnt(8)
	s_waitcnt lgkmcnt(0)
	v_mfma_f32_16x16x32_bf16 v[186:189], v[66:69], v[150:153], v[186:189]
	v_mfma_f32_16x16x32_bf16 v[186:189], v[78:81], v[154:157], v[186:189]
	s_barrier
	s_setprio 1
	v_mfma_f32_16x16x32_bf16 v[182:185], v[98:101], v[154:157], v[182:185]
	v_mfma_f32_16x16x32_bf16 v[182:185], v[86:89], v[150:153], v[182:185]
	v_mfma_f32_16x16x32_bf16 v[134:137], v[86:89], v[158:161], v[134:137]
	v_mfma_f32_16x16x32_bf16 v[134:137], v[98:101], v[162:165], v[134:137]
	v_mfma_f32_16x16x32_bf16 v[138:141], v[78:81], v[162:165], v[138:141]
	v_mfma_f32_16x16x32_bf16 v[138:141], v[66:69], v[158:161], v[138:141]
	v_mfma_f32_16x16x32_bf16 v[114:117], v[66:69], v[170:173], v[114:117]
	v_mfma_f32_16x16x32_bf16 v[114:117], v[78:81], v[174:177], v[114:117]
	v_mfma_f32_16x16x32_bf16 v[110:113], v[98:101], v[174:177], v[110:113]
	v_mfma_f32_16x16x32_bf16 v[110:113], v[86:89], v[170:173], v[110:113]
	v_mfma_f32_16x16x32_bf16 v[82:85], v[86:89], v[178:181], v[82:85]
	v_mfma_f32_16x16x32_bf16 v[82:85], v[98:101], v[190:193], v[82:85]
	v_mfma_f32_16x16x32_bf16 v[90:93], v[78:81], v[190:193], v[90:93]
	v_mfma_f32_16x16x32_bf16 v[90:93], v[66:69], v[178:181], v[90:93]
	v_mfma_f32_16x16x32_bf16 v[166:169], v[106:109], v[150:153], v[166:169]
	v_mfma_f32_16x16x32_bf16 v[166:169], v[118:121], v[154:157], v[166:169]
	v_mfma_f32_16x16x32_bf16 v[146:149], v[142:145], v[154:157], v[146:149]
	v_mfma_f32_16x16x32_bf16 v[146:149], v[130:133], v[150:153], v[146:149]
	v_mfma_f32_16x16x32_bf16 v[122:125], v[130:133], v[158:161], v[122:125]
	v_mfma_f32_16x16x32_bf16 v[122:125], v[142:145], v[162:165], v[122:125]
	v_mfma_f32_16x16x32_bf16 v[126:129], v[118:121], v[162:165], v[126:129]
	v_mfma_f32_16x16x32_bf16 v[126:129], v[106:109], v[158:161], v[126:129]
	v_mfma_f32_16x16x32_bf16 v[102:105], v[106:109], v[170:173], v[102:105]
	v_mfma_f32_16x16x32_bf16 v[102:105], v[118:121], v[174:177], v[102:105]
	v_mfma_f32_16x16x32_bf16 v[94:97], v[142:145], v[174:177], v[94:97]
	v_mfma_f32_16x16x32_bf16 v[94:97], v[130:133], v[170:173], v[94:97]
	v_mfma_f32_16x16x32_bf16 v[70:73], v[130:133], v[178:181], v[70:73]
	v_mfma_f32_16x16x32_bf16 v[70:73], v[142:145], v[190:193], v[70:73]
	v_mfma_f32_16x16x32_bf16 v[74:77], v[118:121], v[190:193], v[74:77]
	v_mfma_f32_16x16x32_bf16 v[74:77], v[106:109], v[178:181], v[74:77]
	s_setprio 0
	s_barrier
	ds_read_b128 v[150:153], v234 offset:49152
	ds_read_b128 v[154:157], v234 offset:50176
	ds_read_b128 v[158:161], v234 offset:51200
	ds_read_b128 v[162:165], v234 offset:52224
	ds_read_b128 v[170:173], v234 offset:53248
	ds_read_b128 v[174:177], v234 offset:54272
	ds_read_b128 v[178:181], v234 offset:55296
	ds_read_b128 v[190:193], v234 offset:56320
	s_add_i32 s18, s49, s26
	v_lshl_add_u64 v[200:201], v[200:201], 0, s[94:95]
	s_mov_b32 m0, s18
	s_nop 0
	global_load_lds_dwordx4 v[200:201], off
	s_add_i32 m0, s18, 0x2000
	s_add_u32 s18, s22, 0x160080
	v_lshl_add_u64 v[200:201], v[214:215], 0, s[94:95]
	s_addc_u32 s19, s23, 0
	s_add_i32 s22, s50, s26
	global_load_lds_dwordx4 v[200:201], off
	v_lshl_add_u64 v[200:201], s[18:19], 0, v[194:195]
	s_mov_b32 m0, s22
	s_nop 0
	global_load_lds_dwordx4 v[200:201], off
	v_lshl_add_u64 v[200:201], s[18:19], 0, v[204:205]
	s_add_i32 m0, s22, 0x2000
	s_nop 0
	global_load_lds_dwordx4 v[200:201], off
	s_waitcnt vmcnt(6)
	s_waitcnt lgkmcnt(0)
	v_mfma_f32_16x16x32_bf16 v[62:65], v[66:69], v[150:153], v[62:65]
	v_mfma_f32_16x16x32_bf16 v[62:65], v[78:81], v[154:157], v[62:65]
	s_barrier
	s_setprio 1
	v_mfma_f32_16x16x32_bf16 v[58:61], v[98:101], v[154:157], v[58:61]
	v_mfma_f32_16x16x32_bf16 v[58:61], v[86:89], v[150:153], v[58:61]
	v_mfma_f32_16x16x32_bf16 v[42:45], v[86:89], v[158:161], v[42:45]
	v_mfma_f32_16x16x32_bf16 v[42:45], v[98:101], v[162:165], v[42:45]
	v_mfma_f32_16x16x32_bf16 v[46:49], v[78:81], v[162:165], v[46:49]
	v_mfma_f32_16x16x32_bf16 v[46:49], v[66:69], v[158:161], v[46:49]
	v_mfma_f32_16x16x32_bf16 v[30:33], v[66:69], v[170:173], v[30:33]
	v_mfma_f32_16x16x32_bf16 v[30:33], v[78:81], v[174:177], v[30:33]
	v_mfma_f32_16x16x32_bf16 v[26:29], v[98:101], v[174:177], v[26:29]
	v_mfma_f32_16x16x32_bf16 v[26:29], v[86:89], v[170:173], v[26:29]
	v_mfma_f32_16x16x32_bf16 v[10:13], v[86:89], v[178:181], v[10:13]
	v_mfma_f32_16x16x32_bf16 v[10:13], v[98:101], v[190:193], v[10:13]
	s_add_i32 s48, s48, 2
	v_mfma_f32_16x16x32_bf16 v[14:17], v[78:81], v[190:193], v[14:17]
	v_mfma_f32_16x16x32_bf16 v[14:17], v[66:69], v[178:181], v[14:17]
	s_add_u32 s46, s46, 0x100
	v_mfma_f32_16x16x32_bf16 v[54:57], v[106:109], v[150:153], v[54:57]
	v_mfma_f32_16x16x32_bf16 v[54:57], v[118:121], v[154:157], v[54:57]
	s_addc_u32 s47, s47, 0
	v_mfma_f32_16x16x32_bf16 v[50:53], v[142:145], v[154:157], v[50:53]
	v_mfma_f32_16x16x32_bf16 v[50:53], v[130:133], v[150:153], v[50:53]
	s_cmpk_gt_u32 s48, 0x55
	v_mfma_f32_16x16x32_bf16 v[34:37], v[130:133], v[158:161], v[34:37]
	v_mfma_f32_16x16x32_bf16 v[34:37], v[142:145], v[162:165], v[34:37]
	s_mov_b64 s[18:19], s[20:21]
	v_mfma_f32_16x16x32_bf16 v[38:41], v[118:121], v[162:165], v[38:41]
	v_mfma_f32_16x16x32_bf16 v[38:41], v[106:109], v[158:161], v[38:41]
	v_mfma_f32_16x16x32_bf16 v[22:25], v[106:109], v[170:173], v[22:25]
	v_mfma_f32_16x16x32_bf16 v[22:25], v[118:121], v[174:177], v[22:25]
	v_mfma_f32_16x16x32_bf16 v[18:21], v[142:145], v[174:177], v[18:21]
	v_mfma_f32_16x16x32_bf16 v[18:21], v[130:133], v[170:173], v[18:21]
	v_mfma_f32_16x16x32_bf16 v[2:5], v[130:133], v[178:181], v[2:5]
	v_mfma_f32_16x16x32_bf16 v[2:5], v[142:145], v[190:193], v[2:5]
	v_mfma_f32_16x16x32_bf16 v[6:9], v[118:121], v[190:193], v[6:9]
	v_mfma_f32_16x16x32_bf16 v[6:9], v[106:109], v[178:181], v[6:9]
	s_setprio 0
	s_barrier
	s_cbranch_scc0 .LBB0_1441
	s_and_b64 vcc, exec, s[14:15]
	s_cbranch_vccz .LBB0_1444
	s_barrier

.LBB0_1511:
	s_add_u32 vcc_lo, s18, 0xffea0000
	s_addc_u32 vcc_hi, s19, -1
	v_lshl_add_u64 v[198:199], vcc, 0, v[210:211]
	s_mov_b32 m0, s44
	s_nop 0
	global_load_lds_dwordx4 v[198:199], off
	v_lshl_add_u64 v[198:199], vcc, 0, v[212:213]
	s_mov_b32 m0, s45
	s_nop 0
	global_load_lds_dwordx4 v[198:199], off
	ds_read_b128 v[130:133], v235
	ds_read_b128 v[134:137], v235 offset:1024
	ds_read_b128 v[138:141], v235 offset:2048
	ds_read_b128 v[142:145], v235 offset:3072
	ds_read_b128 v[146:149], v235 offset:16384
	ds_read_b128 v[150:153], v235 offset:17408
	ds_read_b128 v[154:157], v235 offset:18432
	ds_read_b128 v[158:161], v235 offset:19456
	ds_read_b128 v[162:165], v237
	ds_read_b128 v[166:169], v237 offset:1024
	ds_read_b128 v[170:173], v237 offset:2048
	ds_read_b128 v[174:177], v237 offset:3072
	ds_read_b128 v[178:181], v237 offset:4096
	ds_read_b128 v[182:185], v237 offset:5120
	ds_read_b128 v[186:189], v237 offset:6144
	ds_read_b128 v[190:193], v237 offset:7168
	s_add_i32 s55, s26, 2
	s_add_u32 s24, s18, 0x100
	s_addc_u32 s25, s19, 0
	s_add_i32 s56, 0, 0x10000
	s_cmp_eq_u32 s15, s26
	s_cselect_b32 s29, s7, s25
	s_cselect_b32 s28, s6, s24
	s_cselect_b32 s27, s17, s54
	s_cselect_b32 s26, s16, s23
	s_add_i32 s57, 0, 0x14000
	v_lshl_add_u64 v[198:199], s[18:19], 0, v[210:211]
	s_add_i32 m0, s40, 0xc000
	s_nop 0
	global_load_lds_dwordx4 v[198:199], off
	v_lshl_add_u64 v[198:199], s[18:19], 0, v[212:213]
	s_add_i32 m0, s40, 0xe000
	s_nop 0
	global_load_lds_dwordx4 v[198:199], off
	s_waitcnt vmcnt(8)
	s_waitcnt lgkmcnt(0)
	v_mfma_f32_16x16x32_bf16 v[126:129], v[130:133], v[162:165], v[126:129]
	v_mfma_f32_16x16x32_bf16 v[126:129], v[134:137], v[166:169], v[126:129]
	s_barrier
	s_setprio 1
	v_mfma_f32_16x16x32_bf16 v[122:125], v[142:145], v[166:169], v[122:125]
	v_mfma_f32_16x16x32_bf16 v[122:125], v[138:141], v[162:165], v[122:125]
	v_mfma_f32_16x16x32_bf16 v[106:109], v[138:141], v[170:173], v[106:109]
	v_mfma_f32_16x16x32_bf16 v[106:109], v[142:145], v[174:177], v[106:109]
	v_mfma_f32_16x16x32_bf16 v[110:113], v[134:137], v[174:177], v[110:113]
	v_mfma_f32_16x16x32_bf16 v[110:113], v[130:133], v[170:173], v[110:113]
	v_mfma_f32_16x16x32_bf16 v[94:97], v[130:133], v[178:181], v[94:97]
	v_mfma_f32_16x16x32_bf16 v[94:97], v[134:137], v[182:185], v[94:97]
	v_mfma_f32_16x16x32_bf16 v[90:93], v[142:145], v[182:185], v[90:93]
	v_mfma_f32_16x16x32_bf16 v[90:93], v[138:141], v[178:181], v[90:93]
	v_mfma_f32_16x16x32_bf16 v[74:77], v[138:141], v[186:189], v[74:77]
	v_mfma_f32_16x16x32_bf16 v[74:77], v[142:145], v[190:193], v[74:77]
	v_mfma_f32_16x16x32_bf16 v[78:81], v[134:137], v[190:193], v[78:81]
	v_mfma_f32_16x16x32_bf16 v[78:81], v[130:133], v[186:189], v[78:81]
	v_mfma_f32_16x16x32_bf16 v[118:121], v[146:149], v[162:165], v[118:121]
	v_mfma_f32_16x16x32_bf16 v[118:121], v[150:153], v[166:169], v[118:121]
	v_mfma_f32_16x16x32_bf16 v[114:117], v[158:161], v[166:169], v[114:117]
	v_mfma_f32_16x16x32_bf16 v[114:117], v[154:157], v[162:165], v[114:117]
	v_mfma_f32_16x16x32_bf16 v[98:101], v[154:157], v[170:173], v[98:101]
	v_mfma_f32_16x16x32_bf16 v[98:101], v[158:161], v[174:177], v[98:101]
	v_mfma_f32_16x16x32_bf16 v[102:105], v[150:153], v[174:177], v[102:105]
	v_mfma_f32_16x16x32_bf16 v[102:105], v[146:149], v[170:173], v[102:105]
	v_mfma_f32_16x16x32_bf16 v[86:89], v[146:149], v[178:181], v[86:89]
	v_mfma_f32_16x16x32_bf16 v[86:89], v[150:153], v[182:185], v[86:89]
	v_mfma_f32_16x16x32_bf16 v[82:85], v[158:161], v[182:185], v[82:85]
	v_mfma_f32_16x16x32_bf16 v[82:85], v[154:157], v[178:181], v[82:85]
	v_mfma_f32_16x16x32_bf16 v[66:69], v[154:157], v[186:189], v[66:69]
	v_mfma_f32_16x16x32_bf16 v[66:69], v[158:161], v[190:193], v[66:69]
	v_mfma_f32_16x16x32_bf16 v[70:73], v[150:153], v[190:193], v[70:73]
	v_mfma_f32_16x16x32_bf16 v[70:73], v[146:149], v[186:189], v[70:73]
	s_setprio 0
	s_barrier
	ds_read_b128 v[162:165], v237 offset:16384
	ds_read_b128 v[166:169], v237 offset:17408
	ds_read_b128 v[170:173], v237 offset:18432
	ds_read_b128 v[174:177], v237 offset:19456
	ds_read_b128 v[178:181], v237 offset:20480
	ds_read_b128 v[182:185], v237 offset:21504
	ds_read_b128 v[186:189], v237 offset:22528
	ds_read_b128 v[190:193], v237 offset:23552
	s_add_i32 s18, s56, s39
	v_lshl_add_u64 v[198:199], s[26:27], 0, v[194:195]
	s_mov_b32 m0, s18
	s_nop 0
	global_load_lds_dwordx4 v[198:199], off
	s_add_i32 m0, s18, 0x2000
	s_add_u32 s18, s26, 0x160000
	v_lshl_add_u64 v[200:201], s[26:27], 0, v[208:209]
	s_addc_u32 s19, s27, 0
	s_add_i32 s56, s57, s39
	global_load_lds_dwordx4 v[200:201], off
	v_lshl_add_u64 v[214:215], s[18:19], 0, v[194:195]
	s_mov_b32 m0, s56
	v_lshl_add_u64 v[216:217], s[28:29], 0, v[206:207]
	global_load_lds_dwordx4 v[214:215], off
	v_lshl_add_u64 v[214:215], s[18:19], 0, v[208:209]
	s_add_i32 m0, s56, 0x2000
	s_nop 0
	global_load_lds_dwordx4 v[214:215], off
	v_lshl_add_u64 v[214:215], s[28:29], 0, v[204:205]
	s_waitcnt vmcnt(6)
	s_waitcnt lgkmcnt(0)
	v_mfma_f32_16x16x32_bf16 v[62:65], v[130:133], v[162:165], v[62:65]
	v_mfma_f32_16x16x32_bf16 v[62:65], v[134:137], v[166:169], v[62:65]
	s_barrier
	s_setprio 1
	v_mfma_f32_16x16x32_bf16 v[58:61], v[142:145], v[166:169], v[58:61]
	v_mfma_f32_16x16x32_bf16 v[58:61], v[138:141], v[162:165], v[58:61]
	v_mfma_f32_16x16x32_bf16 v[42:45], v[138:141], v[170:173], v[42:45]
	v_mfma_f32_16x16x32_bf16 v[42:45], v[142:145], v[174:177], v[42:45]
	v_mfma_f32_16x16x32_bf16 v[46:49], v[134:137], v[174:177], v[46:49]
	v_mfma_f32_16x16x32_bf16 v[46:49], v[130:133], v[170:173], v[46:49]
	v_mfma_f32_16x16x32_bf16 v[30:33], v[130:133], v[178:181], v[30:33]
	v_mfma_f32_16x16x32_bf16 v[30:33], v[134:137], v[182:185], v[30:33]
	v_mfma_f32_16x16x32_bf16 v[26:29], v[142:145], v[182:185], v[26:29]
	v_mfma_f32_16x16x32_bf16 v[26:29], v[138:141], v[178:181], v[26:29]
	v_mfma_f32_16x16x32_bf16 v[10:13], v[138:141], v[186:189], v[10:13]
	v_mfma_f32_16x16x32_bf16 v[10:13], v[142:145], v[190:193], v[10:13]
	v_mfma_f32_16x16x32_bf16 v[14:17], v[134:137], v[190:193], v[14:17]
	v_mfma_f32_16x16x32_bf16 v[14:17], v[130:133], v[186:189], v[14:17]
	v_mfma_f32_16x16x32_bf16 v[54:57], v[146:149], v[162:165], v[54:57]
	v_mfma_f32_16x16x32_bf16 v[54:57], v[150:153], v[166:169], v[54:57]
	v_mfma_f32_16x16x32_bf16 v[50:53], v[158:161], v[166:169], v[50:53]
	v_mfma_f32_16x16x32_bf16 v[50:53], v[154:157], v[162:165], v[50:53]
	v_mfma_f32_16x16x32_bf16 v[34:37], v[154:157], v[170:173], v[34:37]
	v_mfma_f32_16x16x32_bf16 v[34:37], v[158:161], v[174:177], v[34:37]
	v_mfma_f32_16x16x32_bf16 v[38:41], v[150:153], v[174:177], v[38:41]
	v_mfma_f32_16x16x32_bf16 v[38:41], v[146:149], v[170:173], v[38:41]
	v_mfma_f32_16x16x32_bf16 v[22:25], v[146:149], v[178:181], v[22:25]
	v_mfma_f32_16x16x32_bf16 v[22:25], v[150:153], v[182:185], v[22:25]
	v_mfma_f32_16x16x32_bf16 v[18:21], v[158:161], v[182:185], v[18:21]
	v_mfma_f32_16x16x32_bf16 v[18:21], v[154:157], v[178:181], v[18:21]
	v_mfma_f32_16x16x32_bf16 v[2:5], v[154:157], v[186:189], v[2:5]
	v_mfma_f32_16x16x32_bf16 v[2:5], v[158:161], v[190:193], v[2:5]
	v_mfma_f32_16x16x32_bf16 v[6:9], v[150:153], v[190:193], v[6:9]
	v_mfma_f32_16x16x32_bf16 v[6:9], v[146:149], v[186:189], v[6:9]
	s_setprio 0
	s_barrier
	s_mov_b32 m0, s40
	s_nop 0
	global_load_lds_dwordx4 v[214:215], off
	s_mov_b32 m0, s41
	s_nop 0
	global_load_lds_dwordx4 v[216:217], off
	ds_read_b128 v[130:133], v235 offset:32768
	ds_read_b128 v[134:137], v235 offset:33792
	ds_read_b128 v[138:141], v235 offset:34816
	ds_read_b128 v[142:145], v235 offset:35840
	ds_read_b128 v[146:149], v235 offset:49152
	ds_read_b128 v[150:153], v235 offset:50176
	ds_read_b128 v[154:157], v235 offset:51200
	ds_read_b128 v[158:161], v235 offset:52224
	ds_read_b128 v[162:165], v237 offset:32768
	ds_read_b128 v[166:169], v237 offset:33792
	ds_read_b128 v[170:173], v237 offset:34816
	ds_read_b128 v[174:177], v237 offset:35840
	ds_read_b128 v[178:181], v237 offset:36864
	ds_read_b128 v[182:185], v237 offset:37888
	ds_read_b128 v[186:189], v237 offset:38912
	ds_read_b128 v[190:193], v237 offset:39936
	s_add_i32 s56, 0, 0x18000
	s_add_i32 s57, 0, 0x1c000
	s_add_u32 s18, s28, 0x160000
	s_addc_u32 s19, s29, 0
	s_mov_b32 m0, s42
	v_lshl_add_u64 v[218:219], s[18:19], 0, v[204:205]
	global_load_lds_dwordx4 v[218:219], off
	v_lshl_add_u64 v[218:219], s[18:19], 0, v[206:207]
	s_mov_b32 m0, s43
	s_nop 0
	global_load_lds_dwordx4 v[218:219], off
	s_waitcnt vmcnt(8)
	s_waitcnt lgkmcnt(0)
	v_mfma_f32_16x16x32_bf16 v[126:129], v[130:133], v[162:165], v[126:129]
	v_mfma_f32_16x16x32_bf16 v[126:129], v[134:137], v[166:169], v[126:129]
	s_barrier
	s_setprio 1
	v_mfma_f32_16x16x32_bf16 v[122:125], v[142:145], v[166:169], v[122:125]
	v_mfma_f32_16x16x32_bf16 v[122:125], v[138:141], v[162:165], v[122:125]
	v_mfma_f32_16x16x32_bf16 v[106:109], v[138:141], v[170:173], v[106:109]
	v_mfma_f32_16x16x32_bf16 v[106:109], v[142:145], v[174:177], v[106:109]
	v_mfma_f32_16x16x32_bf16 v[110:113], v[134:137], v[174:177], v[110:113]
	v_mfma_f32_16x16x32_bf16 v[110:113], v[130:133], v[170:173], v[110:113]
	v_mfma_f32_16x16x32_bf16 v[94:97], v[130:133], v[178:181], v[94:97]
	v_mfma_f32_16x16x32_bf16 v[94:97], v[134:137], v[182:185], v[94:97]
	v_mfma_f32_16x16x32_bf16 v[90:93], v[142:145], v[182:185], v[90:93]
	v_mfma_f32_16x16x32_bf16 v[90:93], v[138:141], v[178:181], v[90:93]
	v_mfma_f32_16x16x32_bf16 v[74:77], v[138:141], v[186:189], v[74:77]
	v_mfma_f32_16x16x32_bf16 v[74:77], v[142:145], v[190:193], v[74:77]
	v_mfma_f32_16x16x32_bf16 v[78:81], v[134:137], v[190:193], v[78:81]
	v_mfma_f32_16x16x32_bf16 v[78:81], v[130:133], v[186:189], v[78:81]
	v_mfma_f32_16x16x32_bf16 v[118:121], v[146:149], v[162:165], v[118:121]
	v_mfma_f32_16x16x32_bf16 v[118:121], v[150:153], v[166:169], v[118:121]
	v_mfma_f32_16x16x32_bf16 v[114:117], v[158:161], v[166:169], v[114:117]
	v_mfma_f32_16x16x32_bf16 v[114:117], v[154:157], v[162:165], v[114:117]
	v_mfma_f32_16x16x32_bf16 v[98:101], v[154:157], v[170:173], v[98:101]
	v_mfma_f32_16x16x32_bf16 v[98:101], v[158:161], v[174:177], v[98:101]
	v_mfma_f32_16x16x32_bf16 v[102:105], v[150:153], v[174:177], v[102:105]
	v_mfma_f32_16x16x32_bf16 v[102:105], v[146:149], v[170:173], v[102:105]
	v_mfma_f32_16x16x32_bf16 v[86:89], v[146:149], v[178:181], v[86:89]
	v_mfma_f32_16x16x32_bf16 v[86:89], v[150:153], v[182:185], v[86:89]
	v_mfma_f32_16x16x32_bf16 v[82:85], v[158:161], v[182:185], v[82:85]
	v_mfma_f32_16x16x32_bf16 v[82:85], v[154:157], v[178:181], v[82:85]
	v_mfma_f32_16x16x32_bf16 v[66:69], v[154:157], v[186:189], v[66:69]
	v_mfma_f32_16x16x32_bf16 v[66:69], v[158:161], v[190:193], v[66:69]
	v_mfma_f32_16x16x32_bf16 v[70:73], v[150:153], v[190:193], v[70:73]
	v_mfma_f32_16x16x32_bf16 v[70:73], v[146:149], v[186:189], v[70:73]
	s_setprio 0
	s_barrier
	ds_read_b128 v[162:165], v237 offset:49152
	ds_read_b128 v[166:169], v237 offset:50176
	ds_read_b128 v[170:173], v237 offset:51200
	ds_read_b128 v[174:177], v237 offset:52224
	ds_read_b128 v[178:181], v237 offset:53248
	ds_read_b128 v[182:185], v237 offset:54272
	ds_read_b128 v[186:189], v237 offset:55296
	ds_read_b128 v[190:193], v237 offset:56320
	s_add_i32 s18, s56, s39
	v_lshl_add_u64 v[198:199], v[198:199], 0, s[94:95]
	s_mov_b32 m0, s18
	s_nop 0
	global_load_lds_dwordx4 v[198:199], off
	s_add_i32 m0, s18, 0x2000
	s_add_u32 s18, s26, 0x160080
	v_lshl_add_u64 v[198:199], v[200:201], 0, s[94:95]
	s_addc_u32 s19, s27, 0
	s_add_i32 s26, s57, s39
	global_load_lds_dwordx4 v[198:199], off
	v_lshl_add_u64 v[198:199], s[18:19], 0, v[194:195]
	s_mov_b32 m0, s26
	s_nop 0
	global_load_lds_dwordx4 v[198:199], off
	v_lshl_add_u64 v[198:199], s[18:19], 0, v[208:209]
	s_add_i32 m0, s26, 0x2000
	s_nop 0
	global_load_lds_dwordx4 v[198:199], off
	s_waitcnt vmcnt(6)
	s_waitcnt lgkmcnt(0)
	v_mfma_f32_16x16x32_bf16 v[62:65], v[130:133], v[162:165], v[62:65]
	v_mfma_f32_16x16x32_bf16 v[62:65], v[134:137], v[166:169], v[62:65]
	s_barrier
	s_setprio 1
	v_mfma_f32_16x16x32_bf16 v[58:61], v[142:145], v[166:169], v[58:61]
	v_mfma_f32_16x16x32_bf16 v[58:61], v[138:141], v[162:165], v[58:61]
	v_mfma_f32_16x16x32_bf16 v[42:45], v[138:141], v[170:173], v[42:45]
	v_mfma_f32_16x16x32_bf16 v[42:45], v[142:145], v[174:177], v[42:45]
	v_mfma_f32_16x16x32_bf16 v[46:49], v[134:137], v[174:177], v[46:49]
	v_mfma_f32_16x16x32_bf16 v[46:49], v[130:133], v[170:173], v[46:49]
	v_mfma_f32_16x16x32_bf16 v[30:33], v[130:133], v[178:181], v[30:33]
	v_mfma_f32_16x16x32_bf16 v[30:33], v[134:137], v[182:185], v[30:33]
	v_mfma_f32_16x16x32_bf16 v[26:29], v[142:145], v[182:185], v[26:29]
	v_mfma_f32_16x16x32_bf16 v[26:29], v[138:141], v[178:181], v[26:29]
	v_mfma_f32_16x16x32_bf16 v[10:13], v[138:141], v[186:189], v[10:13]
	v_mfma_f32_16x16x32_bf16 v[10:13], v[142:145], v[190:193], v[10:13]
	s_add_u32 s23, s23, 0x100
	v_mfma_f32_16x16x32_bf16 v[14:17], v[134:137], v[190:193], v[14:17]
	v_mfma_f32_16x16x32_bf16 v[14:17], v[130:133], v[186:189], v[14:17]
	s_addc_u32 s54, s54, 0
	v_mfma_f32_16x16x32_bf16 v[54:57], v[146:149], v[162:165], v[54:57]
	v_mfma_f32_16x16x32_bf16 v[54:57], v[150:153], v[166:169], v[54:57]
	s_cmp_ge_i32 s55, s21
	v_mfma_f32_16x16x32_bf16 v[50:53], v[158:161], v[166:169], v[50:53]
	v_mfma_f32_16x16x32_bf16 v[50:53], v[154:157], v[162:165], v[50:53]
	s_mov_b64 s[18:19], s[24:25]
	v_mfma_f32_16x16x32_bf16 v[34:37], v[154:157], v[170:173], v[34:37]
	v_mfma_f32_16x16x32_bf16 v[34:37], v[158:161], v[174:177], v[34:37]
	s_mov_b32 s26, s55
	v_mfma_f32_16x16x32_bf16 v[38:41], v[150:153], v[174:177], v[38:41]
	v_mfma_f32_16x16x32_bf16 v[38:41], v[146:149], v[170:173], v[38:41]
	v_mfma_f32_16x16x32_bf16 v[22:25], v[146:149], v[178:181], v[22:25]
	v_mfma_f32_16x16x32_bf16 v[22:25], v[150:153], v[182:185], v[22:25]
	v_mfma_f32_16x16x32_bf16 v[18:21], v[158:161], v[182:185], v[18:21]
	v_mfma_f32_16x16x32_bf16 v[18:21], v[154:157], v[178:181], v[18:21]
	v_mfma_f32_16x16x32_bf16 v[2:5], v[154:157], v[186:189], v[2:5]
	v_mfma_f32_16x16x32_bf16 v[2:5], v[158:161], v[190:193], v[2:5]
	v_mfma_f32_16x16x32_bf16 v[6:9], v[150:153], v[190:193], v[6:9]
	v_mfma_f32_16x16x32_bf16 v[6:9], v[146:149], v[186:189], v[6:9]
	s_setprio 0
	s_barrier
	s_cbranch_scc0 .LBB0_1511
	s_and_b64 vcc, exec, s[12:13]
	s_cbranch_vccz .LBB0_1514
